# t6 + out-proj epilogues (P3 f32 residual, P7 bf16 residual): residual loads preloaded into dead fragment registers, counted waits no longer cover stores/atomics
# baseline (speedup 1.0000x reference)
; __device__ __forceinline__ unsigned cvt_pk_bf16(float lo, float hi) { unsigned r; asm volatile("v_cvt_pk_bf16_f32 %0, %1, %2" : "=v"(r) : "v"(lo), "v"(hi)); return r; }
;     __device__ __forceinline__ void operator()(const f32x4 (&acc)[2][2][4][2], const Unit& u, int wr, int wc, int fr, int fq) const {
;         typedef unsigned u32x2v __attribute__((ext_vector_type(2)));
;         const int row0 = u.pm * BM + wr * 64 + fr, col0 = u.pn * BM + wc * 32 + 4 * fq;
; #pragma unroll
;         for (int ai = 0; ai < 2; ++ai)
; #pragma unroll
;             for (int m = 0; m < 4; ++m) {
;                 const int row = row0 + ai * HALF + m * 16; const size_t off = (size_t)row * ldc + col0; float s = 0.f;
; #pragma unroll
;                 for (int bj = 0; bj < 2; ++bj)
; #pragma unroll
;                     for (int n = 0; n < 2; ++n) {
;                         f32x4 rsd;
;                         if (residb) { const u32x2v w = *(const u32x2v*)(residb + off + bj * HALF + n * 16); rsd = (f32x4){__builtin_bit_cast(float, w.x << 16), __builtin_bit_cast(float, w.x & 0xffff0000u), __builtin_bit_cast(float, w.y << 16), __builtin_bit_cast(float, w.y & 0xffff0000u)}; }
;                         else rsd = *(const f32x4*)(resid + off + bj * HALF + n * 16);
;                         const f32x4 v = rsd + acc[ai][bj][m][n] * asc;
;                         if (out) *(f32x4*)(out + off + bj * HALF + n * 16) = v;
;                         if (outb) { u32x2v w; w.x = cvt_pk_bf16(v[0], v[1]); w.y = cvt_pk_bf16(v[2], v[3]); *(u32x2v*)(outb + off + bj * HALF + n * 16) = w; }
;                         s += (v[0] * v[0] + v[1] * v[1]) + (v[2] * v[2] + v[3] * v[3]);
;                     }
;                 s += __shfl_xor(s, 16); s += __shfl_xor(s, 32);
;                 if (fq == 0) atomicAdd(ss + row, s);
;                 asm volatile("" ::: "memory");
.LBB0_329:
	v_lshl_add_u32 v2, s28, 8, v163
	v_lshl_or_b32 v0, s30, 8, v198
	v_ashrrev_i32_e32 v3, 31, v2
	v_ashrrev_i32_e32 v1, 31, v0
	v_lshlrev_b64 v[4:5], 12, v[2:3]
	v_readlane_b32 s60, v242, 3
	v_lshl_add_u64 v[8:9], v[4:5], 0, v[0:1]
	v_readlane_b32 s61, v242, 4
	s_nop 15
	s_nop 15
	v_lshl_add_u64 v[12:13], v[8:9], 1, s[10:11]
	v_readlane_b32 s62, v242, 5
	v_lshl_add_u64 v[10:11], v[8:9], 2, s[60:61]
	global_load_dwordx4 v[174:177], v[10:11], off
	global_load_dwordx4 v[178:181], v[10:11], off offset:64
	global_load_dwordx4 v[202:205], v[10:11], off offset:512
	global_load_dwordx4 v[206:209], v[10:11], off offset:576
	v_add_co_u32_e32 v222, vcc, 0x40000, v10
	s_nop 1
	v_addc_co_u32_e32 v223, vcc, 0, v11, vcc
	global_load_dwordx4 v[210:213], v[222:223], off
	global_load_dwordx4 v[214:217], v[222:223], off offset:64
	global_load_dwordx4 v[218:221], v[222:223], off offset:512
	global_load_dwordx4 v[222:225], v[222:223], off offset:576
	v_add_co_u32_e32 v238, vcc, 0x80000, v10
	s_nop 1
	v_addc_co_u32_e32 v239, vcc, 0, v11, vcc
	global_load_dwordx4 v[226:229], v[238:239], off
	global_load_dwordx4 v[230:233], v[238:239], off offset:64
	global_load_dwordx4 v[234:237], v[238:239], off offset:512
	global_load_dwordx4 v[238:241], v[238:239], off offset:576
	v_add_co_u32_e32 v28, vcc, 0xc0000, v10
	s_nop 1
	v_addc_co_u32_e32 v29, vcc, 0, v11, vcc
	global_load_dwordx4 v[244:247], v[28:29], off
	global_load_dwordx4 v[248:251], v[28:29], off offset:64
	global_load_dwordx4 v[252:255], v[28:29], off offset:512
	global_load_dwordx4 v[28:31], v[28:29], off offset:576
	s_waitcnt vmcnt(12)
	v_mov_b32_e32 v4, v174
	v_mov_b32_e32 v5, v175
	v_mov_b32_e32 v6, v176
	v_mov_b32_e32 v7, v177
	v_readlane_b32 s63, v242, 6
	v_readlane_b32 s64, v242, 7
	v_readlane_b32 s65, v242, 8
	v_readlane_b32 s66, v242, 9
	v_readlane_b32 s67, v242, 10
	v_readlane_b32 s68, v242, 11
	v_readlane_b32 s69, v242, 12
	v_readlane_b32 s70, v242, 13
	v_readlane_b32 s71, v242, 14
	v_readlane_b32 s72, v242, 15
	v_readlane_b32 s73, v242, 16
	v_readlane_b32 s74, v242, 17
	v_readlane_b32 s75, v242, 18
	v_pk_fma_f32 v[14:15], v[158:159], s[18:19], v[6:7] op_sel_hi:[1,0,1]
	v_pk_fma_f32 v[16:17], v[156:157], s[18:19], v[4:5] op_sel_hi:[1,0,1]
	s_nop 0
	v_cvt_pk_bf16_f32 v4, v16, v17
	v_cvt_pk_bf16_f32 v5, v14, v15
	global_store_dwordx2 v[12:13], v[4:5], off
	s_nop 1
	v_mov_b32_e32 v4, v178
	v_mov_b32_e32 v5, v179
	v_mov_b32_e32 v6, v180
	v_mov_b32_e32 v7, v181
	v_mul_f32_e32 v17, v17, v17
	v_mul_f32_e32 v14, v14, v14
	v_fmac_f32_e32 v17, v16, v16
	v_fmac_f32_e32 v14, v15, v15
	v_add_f32_e32 v14, v17, v14
	v_pk_fma_f32 v[18:19], v[154:155], s[18:19], v[6:7] op_sel_hi:[1,0,1]
	v_pk_fma_f32 v[20:21], v[152:153], s[18:19], v[4:5] op_sel_hi:[1,0,1]
	v_mul_f32_e32 v16, v18, v18
	v_cvt_pk_bf16_f32 v4, v20, v21
	v_cvt_pk_bf16_f32 v5, v18, v19
	global_store_dwordx2 v[12:13], v[4:5], off offset:32
	s_nop 1
	v_mov_b32_e32 v4, v202
	v_mov_b32_e32 v5, v203
	v_mov_b32_e32 v6, v204
	v_mov_b32_e32 v7, v205
	v_mul_f32_e32 v15, v21, v21
	v_fmac_f32_e32 v15, v20, v20
	v_fmac_f32_e32 v16, v19, v19
	v_add_f32_e32 v15, v15, v16
	v_add_f32_e32 v14, v14, v15
	v_pk_fma_f32 v[22:23], v[150:151], s[18:19], v[6:7] op_sel_hi:[1,0,1]
	v_pk_fma_f32 v[4:5], v[148:149], s[18:19], v[4:5] op_sel_hi:[1,0,1]
	v_mul_f32_e32 v15, v22, v22
	v_cvt_pk_bf16_f32 v6, v4, v5
	v_cvt_pk_bf16_f32 v7, v22, v23
	global_store_dwordx2 v[12:13], v[6:7], off offset:256
	s_nop 1
	v_mov_b32_e32 v8, v206
	v_mov_b32_e32 v9, v207
	v_mov_b32_e32 v10, v208
	v_mov_b32_e32 v11, v209
	v_mul_f32_e32 v5, v5, v5
	v_fmac_f32_e32 v5, v4, v4
	v_fmac_f32_e32 v15, v23, v23
	v_and_b32_e32 v7, 64, v200
	v_add_f32_e32 v4, v5, v15
	v_xor_b32_e32 v6, 16, v200
	v_add_u32_e32 v7, 64, v7
	v_add_f32_e32 v4, v14, v4
	v_cmp_lt_i32_e32 vcc, v6, v7
	v_pk_fma_f32 v[10:11], v[146:147], s[18:19], v[10:11] op_sel_hi:[1,0,1]
	v_pk_fma_f32 v[8:9], v[144:145], s[18:19], v[8:9] op_sel_hi:[1,0,1]
	v_mul_f32_e32 v14, v10, v10
	v_mul_f32_e32 v5, v9, v9
	v_fmac_f32_e32 v5, v8, v8
	v_fmac_f32_e32 v14, v11, v11
	v_cndmask_b32_e32 v6, v200, v6, vcc
	v_add_f32_e32 v5, v5, v14
	v_lshlrev_b32_e32 v6, 2, v6
	v_add_f32_e32 v4, v4, v5
	ds_bpermute_b32 v5, v6, v4
	v_xor_b32_e32 v14, 32, v200
	v_cmp_lt_i32_e32 vcc, v14, v7
	v_cvt_pk_bf16_f32 v8, v8, v9
	v_cvt_pk_bf16_f32 v9, v10, v11
	s_waitcnt lgkmcnt(0)
	v_add_f32_e32 v4, v4, v5
	global_store_dwordx2 v[12:13], v[8:9], off offset:288
	v_cndmask_b32_e32 v7, v200, v14, vcc
	v_lshlrev_b32_e32 v7, 2, v7
	ds_bpermute_b32 v5, v7, v4
	s_and_saveexec_b64 s[28:29], s[0:1]
	s_cbranch_execz .LBB0_331
	v_lshl_add_u64 v[8:9], v[2:3], 2, s[12:13]
	s_waitcnt lgkmcnt(0)
	v_add_f32_e32 v3, v4, v5
	global_atomic_add_f32 v[8:9], v3, off
; __device__ __forceinline__ unsigned cvt_pk_bf16(float lo, float hi) { unsigned r; asm volatile("v_cvt_pk_bf16_f32 %0, %1, %2" : "=v"(r) : "v"(lo), "v"(hi)); return r; }
;     __device__ __forceinline__ void operator()(const f32x4 (&acc)[2][2][4][2], const Unit& u, int wr, int wc, int fr, int fq) const {
;     ...
;             for (int m = 0; m < 4; ++m) {
;                 const int row = row0 + ai * HALF + m * 16; const size_t off = (size_t)row * ldc + col0; float s = 0.f;
; #pragma unroll
;                 for (int bj = 0; bj < 2; ++bj)
; #pragma unroll
;                     for (int n = 0; n < 2; ++n) {
;                         f32x4 rsd;
;                         if (residb) { const u32x2v w = *(const u32x2v*)(residb + off + bj * HALF + n * 16); rsd = (f32x4){__builtin_bit_cast(float, w.x << 16), __builtin_bit_cast(float, w.x & 0xffff0000u), __builtin_bit_cast(float, w.y << 16), __builtin_bit_cast(float, w.y & 0xffff0000u)}; }
;                         else rsd = *(const f32x4*)(resid + off + bj * HALF + n * 16);
;                         const f32x4 v = rsd + acc[ai][bj][m][n] * asc;
;                         if (out) *(f32x4*)(out + off + bj * HALF + n * 16) = v;
;                         if (outb) { u32x2v w; w.x = cvt_pk_bf16(v[0], v[1]); w.y = cvt_pk_bf16(v[2], v[3]); *(u32x2v*)(outb + off + bj * HALF + n * 16) = w; }
;                         s += (v[0] * v[0] + v[1] * v[1]) + (v[2] * v[2] + v[3] * v[3]);
;                     }
;                 s += __shfl_xor(s, 16); s += __shfl_xor(s, 32);
;                 if (fq == 0) atomicAdd(ss + row, s);
;                 asm volatile("" ::: "memory");
.LBB0_331:
	s_or_b64 exec, exec, s[28:29]
	v_or_b32_e32 v4, 16, v2
	s_waitcnt lgkmcnt(0)
	v_ashrrev_i32_e32 v5, 31, v4
	v_lshlrev_b64 v[8:9], 12, v[4:5]
	v_readlane_b32 s60, v242, 3
	v_lshl_add_u64 v[12:13], v[8:9], 0, v[0:1]
	v_readlane_b32 s61, v242, 4
	v_readlane_b32 s62, v242, 5
	v_readlane_b32 s63, v242, 6
	v_lshl_add_u64 v[14:15], v[12:13], 2, s[60:61]
	s_waitcnt vmcnt(12)
	v_mov_b32_e32 v8, v210
	v_mov_b32_e32 v9, v211
	v_mov_b32_e32 v10, v212
	v_mov_b32_e32 v11, v213
	v_lshl_add_u64 v[12:13], v[12:13], 1, s[10:11]
	v_readlane_b32 s64, v242, 7
	v_readlane_b32 s65, v242, 8
	v_readlane_b32 s66, v242, 9
	v_readlane_b32 s67, v242, 10
	v_readlane_b32 s68, v242, 11
	v_readlane_b32 s69, v242, 12
	v_readlane_b32 s70, v242, 13
	v_readlane_b32 s71, v242, 14
	v_readlane_b32 s72, v242, 15
	v_readlane_b32 s73, v242, 16
	v_readlane_b32 s74, v242, 17
	v_readlane_b32 s75, v242, 18
	v_pk_fma_f32 v[16:17], v[142:143], s[18:19], v[10:11] op_sel_hi:[1,0,1]
	v_pk_fma_f32 v[18:19], v[140:141], s[18:19], v[8:9] op_sel_hi:[1,0,1]
	s_nop 0
	v_cvt_pk_bf16_f32 v8, v18, v19
	v_cvt_pk_bf16_f32 v9, v16, v17
	global_store_dwordx2 v[12:13], v[8:9], off
	s_nop 1
	v_mov_b32_e32 v8, v214
	v_mov_b32_e32 v9, v215
	v_mov_b32_e32 v10, v216
	v_mov_b32_e32 v11, v217
	v_mul_f32_e32 v3, v19, v19
	v_fmac_f32_e32 v3, v18, v18
	v_pk_fma_f32 v[20:21], v[138:139], s[18:19], v[10:11] op_sel_hi:[1,0,1]
	v_pk_fma_f32 v[22:23], v[136:137], s[18:19], v[8:9] op_sel_hi:[1,0,1]
	s_nop 0
	v_cvt_pk_bf16_f32 v8, v22, v23
	v_cvt_pk_bf16_f32 v9, v20, v21
	global_store_dwordx2 v[12:13], v[8:9], off offset:32
	s_nop 1
	v_mov_b32_e32 v8, v218
	v_mov_b32_e32 v9, v219
	v_mov_b32_e32 v10, v220
	v_mov_b32_e32 v11, v221
	v_pk_fma_f32 v[24:25], v[134:135], s[18:19], v[10:11] op_sel_hi:[1,0,1]
	v_pk_fma_f32 v[26:27], v[132:133], s[18:19], v[8:9] op_sel_hi:[1,0,1]
	s_nop 0
	v_cvt_pk_bf16_f32 v8, v26, v27
	v_cvt_pk_bf16_f32 v9, v24, v25
	global_store_dwordx2 v[12:13], v[8:9], off offset:256
	s_nop 1
	v_mov_b32_e32 v8, v222
	v_mov_b32_e32 v9, v223
	v_mov_b32_e32 v10, v224
	v_mov_b32_e32 v11, v225
	v_mul_f32_e32 v14, v16, v16
	v_fmac_f32_e32 v14, v17, v17
	v_add_f32_e32 v3, v3, v14
	v_mul_f32_e32 v14, v23, v23
	v_mul_f32_e32 v15, v20, v20
	v_fmac_f32_e32 v14, v22, v22
	v_fmac_f32_e32 v15, v21, v21
	v_add_f32_e32 v14, v14, v15
	v_add_f32_e32 v3, v3, v14
	v_mul_f32_e32 v14, v27, v27
	v_mul_f32_e32 v15, v24, v24
	v_fmac_f32_e32 v14, v26, v26
	v_fmac_f32_e32 v15, v25, v25
	v_add_f32_e32 v14, v14, v15
	v_add_f32_e32 v3, v3, v14
	v_pk_fma_f32 v[10:11], v[130:131], s[18:19], v[10:11] op_sel_hi:[1,0,1]
	v_pk_fma_f32 v[14:15], v[128:129], s[18:19], v[8:9] op_sel_hi:[1,0,1]
	v_mul_f32_e32 v9, v10, v10
	v_mul_f32_e32 v8, v15, v15
	v_fmac_f32_e32 v8, v14, v14
	v_fmac_f32_e32 v9, v11, v11
	v_add_f32_e32 v8, v8, v9
	v_add_f32_e32 v3, v3, v8
	ds_bpermute_b32 v8, v6, v3
	v_cvt_pk_bf16_f32 v14, v14, v15
	v_cvt_pk_bf16_f32 v15, v10, v11
	global_store_dwordx2 v[12:13], v[14:15], off offset:288
	s_waitcnt lgkmcnt(0)
	v_add_f32_e32 v3, v3, v8
	ds_bpermute_b32 v8, v7, v3
	s_and_saveexec_b64 s[28:29], s[0:1]
	s_cbranch_execz .LBB0_333
	v_lshl_add_u64 v[4:5], v[4:5], 2, s[12:13]
	s_waitcnt lgkmcnt(0)
	v_add_f32_e32 v3, v3, v8
	global_atomic_add_f32 v[4:5], v3, off
.LBB0_333:
	s_or_b64 exec, exec, s[28:29]
	v_or_b32_e32 v4, 32, v2
	v_ashrrev_i32_e32 v5, 31, v4
	s_waitcnt lgkmcnt(0)
	v_lshlrev_b64 v[8:9], 12, v[4:5]
	v_readlane_b32 s60, v242, 3
	v_lshl_add_u64 v[12:13], v[8:9], 0, v[0:1]
	v_readlane_b32 s61, v242, 4
	v_readlane_b32 s62, v242, 5
	v_readlane_b32 s63, v242, 6
	v_lshl_add_u64 v[14:15], v[12:13], 2, s[60:61]
	s_waitcnt vmcnt(12)
	v_mov_b32_e32 v8, v226
	v_mov_b32_e32 v9, v227
	v_mov_b32_e32 v10, v228
	v_mov_b32_e32 v11, v229
	v_lshl_add_u64 v[12:13], v[12:13], 1, s[10:11]
	v_readlane_b32 s64, v242, 7
	v_readlane_b32 s65, v242, 8
	v_readlane_b32 s66, v242, 9
	v_readlane_b32 s67, v242, 10
	v_readlane_b32 s68, v242, 11
	v_readlane_b32 s69, v242, 12
	v_readlane_b32 s70, v242, 13
	v_readlane_b32 s71, v242, 14
	v_readlane_b32 s72, v242, 15
	v_readlane_b32 s73, v242, 16
	v_readlane_b32 s74, v242, 17
	v_readlane_b32 s75, v242, 18
	v_pk_fma_f32 v[16:17], v[126:127], s[18:19], v[10:11] op_sel_hi:[1,0,1]
	v_pk_fma_f32 v[18:19], v[124:125], s[18:19], v[8:9] op_sel_hi:[1,0,1]
	s_nop 0
	v_cvt_pk_bf16_f32 v8, v18, v19
	v_cvt_pk_bf16_f32 v9, v16, v17
	global_store_dwordx2 v[12:13], v[8:9], off
	s_nop 1
	v_mov_b32_e32 v8, v230
	v_mov_b32_e32 v9, v231
	v_mov_b32_e32 v10, v232
	v_mov_b32_e32 v11, v233
	v_mul_f32_e32 v3, v19, v19
	v_fmac_f32_e32 v3, v18, v18
	v_pk_fma_f32 v[20:21], v[122:123], s[18:19], v[10:11] op_sel_hi:[1,0,1]
	v_pk_fma_f32 v[22:23], v[120:121], s[18:19], v[8:9] op_sel_hi:[1,0,1]
	s_nop 0
	v_cvt_pk_bf16_f32 v8, v22, v23
	v_cvt_pk_bf16_f32 v9, v20, v21
	global_store_dwordx2 v[12:13], v[8:9], off offset:32
	s_nop 1
	v_mov_b32_e32 v8, v234
	v_mov_b32_e32 v9, v235
	v_mov_b32_e32 v10, v236
	v_mov_b32_e32 v11, v237
	v_pk_fma_f32 v[24:25], v[118:119], s[18:19], v[10:11] op_sel_hi:[1,0,1]
	v_pk_fma_f32 v[26:27], v[116:117], s[18:19], v[8:9] op_sel_hi:[1,0,1]
	s_nop 0
	v_cvt_pk_bf16_f32 v8, v26, v27
	v_cvt_pk_bf16_f32 v9, v24, v25
	global_store_dwordx2 v[12:13], v[8:9], off offset:256
	s_nop 1
	v_mov_b32_e32 v8, v238
	v_mov_b32_e32 v9, v239
	v_mov_b32_e32 v10, v240
	v_mov_b32_e32 v11, v241
	v_mul_f32_e32 v14, v16, v16
	v_fmac_f32_e32 v14, v17, v17
	v_add_f32_e32 v3, v3, v14
	v_mul_f32_e32 v14, v23, v23
	v_mul_f32_e32 v15, v20, v20
	v_fmac_f32_e32 v14, v22, v22
	v_fmac_f32_e32 v15, v21, v21
	v_add_f32_e32 v14, v14, v15
	v_add_f32_e32 v3, v3, v14
	v_mul_f32_e32 v14, v27, v27
	v_mul_f32_e32 v15, v24, v24
	v_fmac_f32_e32 v14, v26, v26
	v_fmac_f32_e32 v15, v25, v25
	v_add_f32_e32 v14, v14, v15
	v_add_f32_e32 v3, v3, v14
	v_pk_fma_f32 v[10:11], v[114:115], s[18:19], v[10:11] op_sel_hi:[1,0,1]
	v_pk_fma_f32 v[14:15], v[112:113], s[18:19], v[8:9] op_sel_hi:[1,0,1]
	v_mul_f32_e32 v9, v10, v10
	v_mul_f32_e32 v8, v15, v15
	v_fmac_f32_e32 v8, v14, v14
	v_fmac_f32_e32 v9, v11, v11
	v_add_f32_e32 v8, v8, v9
	v_add_f32_e32 v3, v3, v8
	ds_bpermute_b32 v8, v6, v3
	v_cvt_pk_bf16_f32 v14, v14, v15
	v_cvt_pk_bf16_f32 v15, v10, v11
	global_store_dwordx2 v[12:13], v[14:15], off offset:288
	s_waitcnt lgkmcnt(0)
	v_add_f32_e32 v3, v3, v8
	ds_bpermute_b32 v8, v7, v3
	s_and_saveexec_b64 s[28:29], s[0:1]
	s_cbranch_execz .LBB0_335
	v_lshl_add_u64 v[4:5], v[4:5], 2, s[12:13]
	s_waitcnt lgkmcnt(0)
	v_add_f32_e32 v3, v3, v8
	global_atomic_add_f32 v[4:5], v3, off
; __device__ __forceinline__ unsigned cvt_pk_bf16(float lo, float hi) { unsigned r; asm volatile("v_cvt_pk_bf16_f32 %0, %1, %2" : "=v"(r) : "v"(lo), "v"(hi)); return r; }
;     __device__ __forceinline__ void operator()(const f32x4 (&acc)[2][2][4][2], const Unit& u, int wr, int wc, int fr, int fq) const {
;     ...
;             for (int m = 0; m < 4; ++m) {
;                 const int row = row0 + ai * HALF + m * 16; const size_t off = (size_t)row * ldc + col0; float s = 0.f;
; #pragma unroll
;                 for (int bj = 0; bj < 2; ++bj)
; #pragma unroll
;                     for (int n = 0; n < 2; ++n) {
;                         f32x4 rsd;
;                         if (residb) { const u32x2v w = *(const u32x2v*)(residb + off + bj * HALF + n * 16); rsd = (f32x4){__builtin_bit_cast(float, w.x << 16), __builtin_bit_cast(float, w.x & 0xffff0000u), __builtin_bit_cast(float, w.y << 16), __builtin_bit_cast(float, w.y & 0xffff0000u)}; }
;                         else rsd = *(const f32x4*)(resid + off + bj * HALF + n * 16);
;                         const f32x4 v = rsd + acc[ai][bj][m][n] * asc;
;                         if (out) *(f32x4*)(out + off + bj * HALF + n * 16) = v;
;                         if (outb) { u32x2v w; w.x = cvt_pk_bf16(v[0], v[1]); w.y = cvt_pk_bf16(v[2], v[3]); *(u32x2v*)(outb + off + bj * HALF + n * 16) = w; }
;                         s += (v[0] * v[0] + v[1] * v[1]) + (v[2] * v[2] + v[3] * v[3]);
;                     }
;                 s += __shfl_xor(s, 16); s += __shfl_xor(s, 32);
;                 if (fq == 0) atomicAdd(ss + row, s);
;                 asm volatile("" ::: "memory");
.LBB0_335:
	s_or_b64 exec, exec, s[28:29]
	v_or_b32_e32 v4, 48, v2
	v_ashrrev_i32_e32 v5, 31, v4
	s_waitcnt lgkmcnt(0)
	v_lshlrev_b64 v[8:9], 12, v[4:5]
	v_readlane_b32 s60, v242, 3
	v_lshl_add_u64 v[12:13], v[8:9], 0, v[0:1]
	v_readlane_b32 s61, v242, 4
	v_readlane_b32 s62, v242, 5
	v_readlane_b32 s63, v242, 6
	v_lshl_add_u64 v[14:15], v[12:13], 2, s[60:61]
	s_waitcnt vmcnt(12)
	v_mov_b32_e32 v8, v244
	v_mov_b32_e32 v9, v245
	v_mov_b32_e32 v10, v246
	v_mov_b32_e32 v11, v247
	v_lshl_add_u64 v[12:13], v[12:13], 1, s[10:11]
	v_readlane_b32 s64, v242, 7
	v_readlane_b32 s65, v242, 8
	v_readlane_b32 s66, v242, 9
	v_readlane_b32 s67, v242, 10
	v_readlane_b32 s68, v242, 11
	v_readlane_b32 s69, v242, 12
	v_readlane_b32 s70, v242, 13
	v_readlane_b32 s71, v242, 14
	v_readlane_b32 s72, v242, 15
	v_readlane_b32 s73, v242, 16
	v_readlane_b32 s74, v242, 17
	v_readlane_b32 s75, v242, 18
	v_pk_fma_f32 v[16:17], v[110:111], s[18:19], v[10:11] op_sel_hi:[1,0,1]
	v_pk_fma_f32 v[18:19], v[108:109], s[18:19], v[8:9] op_sel_hi:[1,0,1]
	s_nop 0
	v_cvt_pk_bf16_f32 v8, v18, v19
	v_cvt_pk_bf16_f32 v9, v16, v17
	global_store_dwordx2 v[12:13], v[8:9], off
	s_nop 1
	v_mov_b32_e32 v8, v248
	v_mov_b32_e32 v9, v249
	v_mov_b32_e32 v10, v250
	v_mov_b32_e32 v11, v251
	v_mul_f32_e32 v3, v19, v19
	v_fmac_f32_e32 v3, v18, v18
	v_pk_fma_f32 v[20:21], v[106:107], s[18:19], v[10:11] op_sel_hi:[1,0,1]
	v_pk_fma_f32 v[22:23], v[104:105], s[18:19], v[8:9] op_sel_hi:[1,0,1]
	s_nop 0
	v_cvt_pk_bf16_f32 v8, v22, v23
	v_cvt_pk_bf16_f32 v9, v20, v21
	global_store_dwordx2 v[12:13], v[8:9], off offset:32
	s_nop 1
	v_mov_b32_e32 v8, v252
	v_mov_b32_e32 v9, v253
	v_mov_b32_e32 v10, v254
	v_mov_b32_e32 v11, v255
	v_pk_fma_f32 v[24:25], v[102:103], s[18:19], v[10:11] op_sel_hi:[1,0,1]
	v_pk_fma_f32 v[26:27], v[100:101], s[18:19], v[8:9] op_sel_hi:[1,0,1]
	s_nop 0
	v_cvt_pk_bf16_f32 v8, v26, v27
	v_cvt_pk_bf16_f32 v9, v24, v25
	global_store_dwordx2 v[12:13], v[8:9], off offset:256
	s_nop 1
	v_mov_b32_e32 v8, v28
	v_mov_b32_e32 v9, v29
	v_mov_b32_e32 v10, v30
	v_mov_b32_e32 v11, v31
	v_mul_f32_e32 v14, v16, v16
	v_fmac_f32_e32 v14, v17, v17
	v_add_f32_e32 v3, v3, v14
	v_mul_f32_e32 v14, v23, v23
	v_mul_f32_e32 v15, v20, v20
	v_fmac_f32_e32 v14, v22, v22
	v_fmac_f32_e32 v15, v21, v21
	v_add_f32_e32 v14, v14, v15
	v_add_f32_e32 v3, v3, v14
	v_mul_f32_e32 v14, v27, v27
	v_mul_f32_e32 v15, v24, v24
	v_fmac_f32_e32 v14, v26, v26
	v_fmac_f32_e32 v15, v25, v25
	v_add_f32_e32 v14, v14, v15
	v_add_f32_e32 v3, v3, v14
	v_pk_fma_f32 v[10:11], v[98:99], s[18:19], v[10:11] op_sel_hi:[1,0,1]
	v_pk_fma_f32 v[14:15], v[96:97], s[18:19], v[8:9] op_sel_hi:[1,0,1]
	v_mul_f32_e32 v9, v10, v10
	v_mul_f32_e32 v8, v15, v15
	v_fmac_f32_e32 v8, v14, v14
	v_fmac_f32_e32 v9, v11, v11
	v_add_f32_e32 v8, v8, v9
	v_add_f32_e32 v3, v3, v8
	ds_bpermute_b32 v8, v6, v3
	v_cvt_pk_bf16_f32 v14, v14, v15
	v_cvt_pk_bf16_f32 v15, v10, v11
	global_store_dwordx2 v[12:13], v[14:15], off offset:288
	s_waitcnt lgkmcnt(0)
	v_add_f32_e32 v3, v3, v8
	ds_bpermute_b32 v8, v7, v3
	s_and_saveexec_b64 s[28:29], s[0:1]
	s_cbranch_execz .LBB0_337
	v_lshl_add_u64 v[4:5], v[4:5], 2, s[12:13]
	s_waitcnt lgkmcnt(0)
	v_add_f32_e32 v3, v3, v8
	global_atomic_add_f32 v[4:5], v3, off
.LBB0_337:
	s_or_b64 exec, exec, s[28:29]
	v_add_u32_e32 v4, 0x80, v2
	v_ashrrev_i32_e32 v5, 31, v4
	s_waitcnt lgkmcnt(0)
	v_lshlrev_b64 v[8:9], 12, v[4:5]
	v_readlane_b32 s60, v242, 3
	v_lshl_add_u64 v[12:13], v[8:9], 0, v[0:1]
	v_readlane_b32 s61, v242, 4
	v_readlane_b32 s62, v242, 5
	v_readlane_b32 s63, v242, 6
	v_lshl_add_u64 v[14:15], v[12:13], 2, s[60:61]
	global_load_dwordx4 v[174:177], v[14:15], off
	global_load_dwordx4 v[178:181], v[14:15], off offset:64
	global_load_dwordx4 v[202:205], v[14:15], off offset:512
	global_load_dwordx4 v[206:209], v[14:15], off offset:576
	v_add_co_u32_e32 v222, vcc, 0x40000, v14
	s_nop 1
	v_addc_co_u32_e32 v223, vcc, 0, v15, vcc
	global_load_dwordx4 v[210:213], v[222:223], off
	global_load_dwordx4 v[214:217], v[222:223], off offset:64
	global_load_dwordx4 v[218:221], v[222:223], off offset:512
	global_load_dwordx4 v[222:225], v[222:223], off offset:576
	v_add_co_u32_e32 v238, vcc, 0x80000, v14
	s_nop 1
	v_addc_co_u32_e32 v239, vcc, 0, v15, vcc
	global_load_dwordx4 v[226:229], v[238:239], off
	global_load_dwordx4 v[230:233], v[238:239], off offset:64
	global_load_dwordx4 v[234:237], v[238:239], off offset:512
	global_load_dwordx4 v[238:241], v[238:239], off offset:576
	v_add_co_u32_e32 v28, vcc, 0xc0000, v14
	s_nop 1
	v_addc_co_u32_e32 v29, vcc, 0, v15, vcc
	global_load_dwordx4 v[244:247], v[28:29], off
	global_load_dwordx4 v[248:251], v[28:29], off offset:64
	global_load_dwordx4 v[252:255], v[28:29], off offset:512
	global_load_dwordx4 v[28:31], v[28:29], off offset:576
	s_waitcnt vmcnt(12)
; __device__ __forceinline__ unsigned cvt_pk_bf16(float lo, float hi) { unsigned r; asm volatile("v_cvt_pk_bf16_f32 %0, %1, %2" : "=v"(r) : "v"(lo), "v"(hi)); return r; }
;     __device__ __forceinline__ void operator()(const f32x4 (&acc)[2][2][4][2], const Unit& u, int wr, int wc, int fr, int fq) const {
;     ...
;             for (int m = 0; m < 4; ++m) {
;                 const int row = row0 + ai * HALF + m * 16; const size_t off = (size_t)row * ldc + col0; float s = 0.f;
; #pragma unroll
;                 for (int bj = 0; bj < 2; ++bj)
; #pragma unroll
;                     for (int n = 0; n < 2; ++n) {
;                         f32x4 rsd;
;                         if (residb) { const u32x2v w = *(const u32x2v*)(residb + off + bj * HALF + n * 16); rsd = (f32x4){__builtin_bit_cast(float, w.x << 16), __builtin_bit_cast(float, w.x & 0xffff0000u), __builtin_bit_cast(float, w.y << 16), __builtin_bit_cast(float, w.y & 0xffff0000u)}; }
;                         else rsd = *(const f32x4*)(resid + off + bj * HALF + n * 16);
;                         const f32x4 v = rsd + acc[ai][bj][m][n] * asc;
;                         if (out) *(f32x4*)(out + off + bj * HALF + n * 16) = v;
;                         if (outb) { u32x2v w; w.x = cvt_pk_bf16(v[0], v[1]); w.y = cvt_pk_bf16(v[2], v[3]); *(u32x2v*)(outb + off + bj * HALF + n * 16) = w; }
;                         s += (v[0] * v[0] + v[1] * v[1]) + (v[2] * v[2] + v[3] * v[3]);
;                     }
;                 s += __shfl_xor(s, 16); s += __shfl_xor(s, 32);
;                 if (fq == 0) atomicAdd(ss + row, s);
;                 asm volatile("" ::: "memory");
	v_mov_b32_e32 v8, v174
	v_mov_b32_e32 v9, v175
	v_mov_b32_e32 v10, v176
	v_mov_b32_e32 v11, v177
	v_lshl_add_u64 v[12:13], v[12:13], 1, s[10:11]
	v_readlane_b32 s64, v242, 7
	v_readlane_b32 s65, v242, 8
	v_readlane_b32 s66, v242, 9
	v_readlane_b32 s67, v242, 10
	v_readlane_b32 s68, v242, 11
	v_readlane_b32 s69, v242, 12
	v_readlane_b32 s70, v242, 13
	v_readlane_b32 s71, v242, 14
	v_readlane_b32 s72, v242, 15
	v_readlane_b32 s73, v242, 16
	v_readlane_b32 s74, v242, 17
	v_readlane_b32 s75, v242, 18
	v_pk_fma_f32 v[16:17], v[94:95], s[18:19], v[10:11] op_sel_hi:[1,0,1]
	v_pk_fma_f32 v[18:19], v[92:93], s[18:19], v[8:9] op_sel_hi:[1,0,1]
	s_nop 0
	v_cvt_pk_bf16_f32 v8, v18, v19
	v_cvt_pk_bf16_f32 v9, v16, v17
	global_store_dwordx2 v[12:13], v[8:9], off
	s_nop 1
	v_mov_b32_e32 v8, v178
	v_mov_b32_e32 v9, v179
	v_mov_b32_e32 v10, v180
	v_mov_b32_e32 v11, v181
	v_mul_f32_e32 v3, v19, v19
	v_fmac_f32_e32 v3, v18, v18
	v_pk_fma_f32 v[20:21], v[90:91], s[18:19], v[10:11] op_sel_hi:[1,0,1]
	v_pk_fma_f32 v[22:23], v[88:89], s[18:19], v[8:9] op_sel_hi:[1,0,1]
	s_nop 0
	v_cvt_pk_bf16_f32 v8, v22, v23
	v_cvt_pk_bf16_f32 v9, v20, v21
	global_store_dwordx2 v[12:13], v[8:9], off offset:32
	s_nop 1
	v_mov_b32_e32 v8, v202
	v_mov_b32_e32 v9, v203
	v_mov_b32_e32 v10, v204
	v_mov_b32_e32 v11, v205
	v_pk_fma_f32 v[24:25], v[86:87], s[18:19], v[10:11] op_sel_hi:[1,0,1]
	v_pk_fma_f32 v[26:27], v[84:85], s[18:19], v[8:9] op_sel_hi:[1,0,1]
	s_nop 0
	v_cvt_pk_bf16_f32 v8, v26, v27
	v_cvt_pk_bf16_f32 v9, v24, v25
	global_store_dwordx2 v[12:13], v[8:9], off offset:256
	s_nop 1
	v_mov_b32_e32 v8, v206
	v_mov_b32_e32 v9, v207
	v_mov_b32_e32 v10, v208
	v_mov_b32_e32 v11, v209
	v_mul_f32_e32 v14, v16, v16
	v_fmac_f32_e32 v14, v17, v17
	v_add_f32_e32 v3, v3, v14
	v_mul_f32_e32 v14, v23, v23
	v_mul_f32_e32 v15, v20, v20
	v_fmac_f32_e32 v14, v22, v22
	v_fmac_f32_e32 v15, v21, v21
	v_add_f32_e32 v14, v14, v15
	v_add_f32_e32 v3, v3, v14
	v_mul_f32_e32 v14, v27, v27
	v_mul_f32_e32 v15, v24, v24
	v_fmac_f32_e32 v14, v26, v26
	v_fmac_f32_e32 v15, v25, v25
	v_add_f32_e32 v14, v14, v15
	v_add_f32_e32 v3, v3, v14
	v_pk_fma_f32 v[10:11], v[82:83], s[18:19], v[10:11] op_sel_hi:[1,0,1]
	v_pk_fma_f32 v[14:15], v[80:81], s[18:19], v[8:9] op_sel_hi:[1,0,1]
	v_mul_f32_e32 v9, v10, v10
	v_mul_f32_e32 v8, v15, v15
	v_fmac_f32_e32 v8, v14, v14
	v_fmac_f32_e32 v9, v11, v11
	v_add_f32_e32 v8, v8, v9
	v_add_f32_e32 v3, v3, v8
	ds_bpermute_b32 v8, v6, v3
	v_cvt_pk_bf16_f32 v14, v14, v15
	v_cvt_pk_bf16_f32 v15, v10, v11
	global_store_dwordx2 v[12:13], v[14:15], off offset:288
	s_waitcnt lgkmcnt(0)
	v_add_f32_e32 v3, v3, v8
	ds_bpermute_b32 v8, v7, v3
	s_and_saveexec_b64 s[28:29], s[0:1]
	s_cbranch_execz .LBB0_339
	v_lshl_add_u64 v[4:5], v[4:5], 2, s[12:13]
	s_waitcnt lgkmcnt(0)
	v_add_f32_e32 v3, v3, v8
	global_atomic_add_f32 v[4:5], v3, off
.LBB0_339:
	s_or_b64 exec, exec, s[28:29]
	v_add_u32_e32 v4, 0x90, v2
	v_ashrrev_i32_e32 v5, 31, v4
	s_waitcnt lgkmcnt(0)
	v_lshlrev_b64 v[8:9], 12, v[4:5]
	v_readlane_b32 s60, v242, 3
	v_lshl_add_u64 v[12:13], v[8:9], 0, v[0:1]
	v_readlane_b32 s61, v242, 4
	v_readlane_b32 s62, v242, 5
	v_readlane_b32 s63, v242, 6
	v_lshl_add_u64 v[14:15], v[12:13], 2, s[60:61]
	s_waitcnt vmcnt(12)
	v_mov_b32_e32 v8, v210
	v_mov_b32_e32 v9, v211
	v_mov_b32_e32 v10, v212
	v_mov_b32_e32 v11, v213
	v_lshl_add_u64 v[12:13], v[12:13], 1, s[10:11]
	v_readlane_b32 s64, v242, 7
	v_readlane_b32 s65, v242, 8
	v_readlane_b32 s66, v242, 9
	v_readlane_b32 s67, v242, 10
	v_readlane_b32 s68, v242, 11
	v_readlane_b32 s69, v242, 12
	v_readlane_b32 s70, v242, 13
	v_readlane_b32 s71, v242, 14
	v_readlane_b32 s72, v242, 15
	v_readlane_b32 s73, v242, 16
	v_readlane_b32 s74, v242, 17
	v_readlane_b32 s75, v242, 18
	v_pk_fma_f32 v[16:17], v[78:79], s[18:19], v[10:11] op_sel_hi:[1,0,1]
	v_pk_fma_f32 v[18:19], v[76:77], s[18:19], v[8:9] op_sel_hi:[1,0,1]
	s_nop 0
	v_cvt_pk_bf16_f32 v8, v18, v19
	v_cvt_pk_bf16_f32 v9, v16, v17
	global_store_dwordx2 v[12:13], v[8:9], off
	s_nop 1
	v_mov_b32_e32 v8, v214
	v_mov_b32_e32 v9, v215
	v_mov_b32_e32 v10, v216
	v_mov_b32_e32 v11, v217
	v_mul_f32_e32 v3, v19, v19
	v_fmac_f32_e32 v3, v18, v18
	v_pk_fma_f32 v[20:21], v[74:75], s[18:19], v[10:11] op_sel_hi:[1,0,1]
	v_pk_fma_f32 v[22:23], v[72:73], s[18:19], v[8:9] op_sel_hi:[1,0,1]
	s_nop 0
	v_cvt_pk_bf16_f32 v8, v22, v23
	v_cvt_pk_bf16_f32 v9, v20, v21
	global_store_dwordx2 v[12:13], v[8:9], off offset:32
	s_nop 1
	v_mov_b32_e32 v8, v218
	v_mov_b32_e32 v9, v219
	v_mov_b32_e32 v10, v220
	v_mov_b32_e32 v11, v221
	v_pk_fma_f32 v[24:25], v[70:71], s[18:19], v[10:11] op_sel_hi:[1,0,1]
	v_pk_fma_f32 v[26:27], v[68:69], s[18:19], v[8:9] op_sel_hi:[1,0,1]
	s_nop 0
	v_cvt_pk_bf16_f32 v8, v26, v27
	v_cvt_pk_bf16_f32 v9, v24, v25
	global_store_dwordx2 v[12:13], v[8:9], off offset:256
	s_nop 1
	v_mov_b32_e32 v8, v222
	v_mov_b32_e32 v9, v223
	v_mov_b32_e32 v10, v224
	v_mov_b32_e32 v11, v225
	v_mul_f32_e32 v14, v16, v16
	v_fmac_f32_e32 v14, v17, v17
	v_add_f32_e32 v3, v3, v14
	v_mul_f32_e32 v14, v23, v23
	v_mul_f32_e32 v15, v20, v20
	v_fmac_f32_e32 v14, v22, v22
	v_fmac_f32_e32 v15, v21, v21
	v_add_f32_e32 v14, v14, v15
	v_add_f32_e32 v3, v3, v14
	v_mul_f32_e32 v14, v27, v27
	v_mul_f32_e32 v15, v24, v24
	v_fmac_f32_e32 v14, v26, v26
	v_fmac_f32_e32 v15, v25, v25
	v_add_f32_e32 v14, v14, v15
	v_add_f32_e32 v3, v3, v14
	v_pk_fma_f32 v[10:11], v[66:67], s[18:19], v[10:11] op_sel_hi:[1,0,1]
	v_pk_fma_f32 v[14:15], v[64:65], s[18:19], v[8:9] op_sel_hi:[1,0,1]
	v_mul_f32_e32 v9, v10, v10
	v_mul_f32_e32 v8, v15, v15
	v_fmac_f32_e32 v8, v14, v14
	v_fmac_f32_e32 v9, v11, v11
	v_add_f32_e32 v8, v8, v9
	v_add_f32_e32 v3, v3, v8
	ds_bpermute_b32 v8, v6, v3
	v_cvt_pk_bf16_f32 v14, v14, v15
	v_cvt_pk_bf16_f32 v15, v10, v11
	global_store_dwordx2 v[12:13], v[14:15], off offset:288
	s_waitcnt lgkmcnt(0)
	v_add_f32_e32 v3, v3, v8
	ds_bpermute_b32 v8, v7, v3
	s_and_saveexec_b64 s[28:29], s[0:1]
	s_cbranch_execz .LBB0_341
	v_lshl_add_u64 v[4:5], v[4:5], 2, s[12:13]
	s_waitcnt lgkmcnt(0)
	v_add_f32_e32 v3, v3, v8
	global_atomic_add_f32 v[4:5], v3, off
; __device__ __forceinline__ unsigned cvt_pk_bf16(float lo, float hi) { unsigned r; asm volatile("v_cvt_pk_bf16_f32 %0, %1, %2" : "=v"(r) : "v"(lo), "v"(hi)); return r; }
;     __device__ __forceinline__ void operator()(const f32x4 (&acc)[2][2][4][2], const Unit& u, int wr, int wc, int fr, int fq) const {
;     ...
;             for (int m = 0; m < 4; ++m) {
;                 const int row = row0 + ai * HALF + m * 16; const size_t off = (size_t)row * ldc + col0; float s = 0.f;
; #pragma unroll
;                 for (int bj = 0; bj < 2; ++bj)
; #pragma unroll
;                     for (int n = 0; n < 2; ++n) {
;                         f32x4 rsd;
;                         if (residb) { const u32x2v w = *(const u32x2v*)(residb + off + bj * HALF + n * 16); rsd = (f32x4){__builtin_bit_cast(float, w.x << 16), __builtin_bit_cast(float, w.x & 0xffff0000u), __builtin_bit_cast(float, w.y << 16), __builtin_bit_cast(float, w.y & 0xffff0000u)}; }
;                         else rsd = *(const f32x4*)(resid + off + bj * HALF + n * 16);
;                         const f32x4 v = rsd + acc[ai][bj][m][n] * asc;
;                         if (out) *(f32x4*)(out + off + bj * HALF + n * 16) = v;
;                         if (outb) { u32x2v w; w.x = cvt_pk_bf16(v[0], v[1]); w.y = cvt_pk_bf16(v[2], v[3]); *(u32x2v*)(outb + off + bj * HALF + n * 16) = w; }
;                         s += (v[0] * v[0] + v[1] * v[1]) + (v[2] * v[2] + v[3] * v[3]);
;                     }
;                 s += __shfl_xor(s, 16); s += __shfl_xor(s, 32);
;                 if (fq == 0) atomicAdd(ss + row, s);
;                 asm volatile("" ::: "memory");
.LBB0_341:
	s_or_b64 exec, exec, s[28:29]
	v_add_u32_e32 v4, 0xa0, v2
	v_ashrrev_i32_e32 v5, 31, v4
	s_waitcnt lgkmcnt(0)
	v_lshlrev_b64 v[8:9], 12, v[4:5]
	v_readlane_b32 s60, v242, 3
	v_lshl_add_u64 v[12:13], v[8:9], 0, v[0:1]
	v_readlane_b32 s61, v242, 4
	v_readlane_b32 s62, v242, 5
	v_readlane_b32 s63, v242, 6
	v_lshl_add_u64 v[14:15], v[12:13], 2, s[60:61]
	s_waitcnt vmcnt(12)
	v_mov_b32_e32 v8, v226
	v_mov_b32_e32 v9, v227
	v_mov_b32_e32 v10, v228
	v_mov_b32_e32 v11, v229
	v_lshl_add_u64 v[12:13], v[12:13], 1, s[10:11]
	v_readlane_b32 s64, v242, 7
	v_readlane_b32 s65, v242, 8
	v_readlane_b32 s66, v242, 9
	v_readlane_b32 s67, v242, 10
	v_readlane_b32 s68, v242, 11
	v_readlane_b32 s69, v242, 12
	v_readlane_b32 s70, v242, 13
	v_readlane_b32 s71, v242, 14
	v_readlane_b32 s72, v242, 15
	v_readlane_b32 s73, v242, 16
	v_readlane_b32 s74, v242, 17
	v_readlane_b32 s75, v242, 18
	v_pk_fma_f32 v[16:17], v[62:63], s[18:19], v[10:11] op_sel_hi:[1,0,1]
	v_pk_fma_f32 v[18:19], v[60:61], s[18:19], v[8:9] op_sel_hi:[1,0,1]
	s_nop 0
	v_cvt_pk_bf16_f32 v8, v18, v19
	v_cvt_pk_bf16_f32 v9, v16, v17
	global_store_dwordx2 v[12:13], v[8:9], off
	s_nop 1
	v_mov_b32_e32 v8, v230
	v_mov_b32_e32 v9, v231
	v_mov_b32_e32 v10, v232
	v_mov_b32_e32 v11, v233
	v_mul_f32_e32 v3, v19, v19
	v_fmac_f32_e32 v3, v18, v18
	v_pk_fma_f32 v[20:21], v[58:59], s[18:19], v[10:11] op_sel_hi:[1,0,1]
	v_pk_fma_f32 v[22:23], v[56:57], s[18:19], v[8:9] op_sel_hi:[1,0,1]
	s_nop 0
	v_cvt_pk_bf16_f32 v8, v22, v23
	v_cvt_pk_bf16_f32 v9, v20, v21
	global_store_dwordx2 v[12:13], v[8:9], off offset:32
	s_nop 1
	v_mov_b32_e32 v8, v234
	v_mov_b32_e32 v9, v235
	v_mov_b32_e32 v10, v236
	v_mov_b32_e32 v11, v237
	v_pk_fma_f32 v[24:25], v[54:55], s[18:19], v[10:11] op_sel_hi:[1,0,1]
	v_pk_fma_f32 v[26:27], v[52:53], s[18:19], v[8:9] op_sel_hi:[1,0,1]
	s_nop 0
	v_cvt_pk_bf16_f32 v8, v26, v27
	v_cvt_pk_bf16_f32 v9, v24, v25
	global_store_dwordx2 v[12:13], v[8:9], off offset:256
	s_nop 1
	v_mov_b32_e32 v8, v238
	v_mov_b32_e32 v9, v239
	v_mov_b32_e32 v10, v240
	v_mov_b32_e32 v11, v241
	v_mul_f32_e32 v14, v16, v16
	v_fmac_f32_e32 v14, v17, v17
	v_add_f32_e32 v3, v3, v14
	v_mul_f32_e32 v14, v23, v23
	v_mul_f32_e32 v15, v20, v20
	v_fmac_f32_e32 v14, v22, v22
	v_fmac_f32_e32 v15, v21, v21
	v_add_f32_e32 v14, v14, v15
	v_add_f32_e32 v3, v3, v14
	v_mul_f32_e32 v14, v27, v27
	v_mul_f32_e32 v15, v24, v24
	v_fmac_f32_e32 v14, v26, v26
	v_fmac_f32_e32 v15, v25, v25
	v_add_f32_e32 v14, v14, v15
	v_add_f32_e32 v3, v3, v14
	v_pk_fma_f32 v[10:11], v[50:51], s[18:19], v[10:11] op_sel_hi:[1,0,1]
	v_pk_fma_f32 v[14:15], v[48:49], s[18:19], v[8:9] op_sel_hi:[1,0,1]
	v_mul_f32_e32 v9, v10, v10
	v_mul_f32_e32 v8, v15, v15
	v_fmac_f32_e32 v8, v14, v14
	v_fmac_f32_e32 v9, v11, v11
	v_add_f32_e32 v8, v8, v9
	v_add_f32_e32 v3, v3, v8
	ds_bpermute_b32 v8, v6, v3
	v_cvt_pk_bf16_f32 v14, v14, v15
	v_cvt_pk_bf16_f32 v15, v10, v11
	global_store_dwordx2 v[12:13], v[14:15], off offset:288
	s_waitcnt lgkmcnt(0)
	v_add_f32_e32 v3, v3, v8
	ds_bpermute_b32 v8, v7, v3
	s_and_saveexec_b64 s[28:29], s[0:1]
	s_cbranch_execz .LBB0_343
	v_lshl_add_u64 v[4:5], v[4:5], 2, s[12:13]
	s_waitcnt lgkmcnt(0)
	v_add_f32_e32 v3, v3, v8
	global_atomic_add_f32 v[4:5], v3, off
.LBB0_343:
	s_or_b64 exec, exec, s[28:29]
	v_add_u32_e32 v2, 0xb0, v2
	v_ashrrev_i32_e32 v3, 31, v2
	v_lshlrev_b64 v[4:5], 12, v[2:3]
	v_readlane_b32 s60, v242, 3
	v_lshl_add_u64 v[0:1], v[4:5], 0, v[0:1]
	v_readlane_b32 s61, v242, 4
	v_lshl_add_u64 v[12:13], v[0:1], 1, s[10:11]
	v_readlane_b32 s62, v242, 5
	v_lshl_add_u64 v[4:5], v[0:1], 2, s[60:61]
	s_waitcnt lgkmcnt(0)
	s_waitcnt vmcnt(12)
	v_mov_b32_e32 v8, v244
	v_mov_b32_e32 v9, v245
	v_mov_b32_e32 v10, v246
	v_mov_b32_e32 v11, v247
	v_readlane_b32 s63, v242, 6
	v_readlane_b32 s64, v242, 7
	v_readlane_b32 s65, v242, 8
	v_readlane_b32 s66, v242, 9
	v_readlane_b32 s67, v242, 10
	v_readlane_b32 s68, v242, 11
	v_readlane_b32 s69, v242, 12
	v_readlane_b32 s70, v242, 13
	v_readlane_b32 s71, v242, 14
	v_readlane_b32 s72, v242, 15
	v_readlane_b32 s73, v242, 16
	v_readlane_b32 s74, v242, 17
	v_readlane_b32 s75, v242, 18
	v_pk_fma_f32 v[0:1], v[46:47], s[18:19], v[10:11] op_sel_hi:[1,0,1]
	v_pk_fma_f32 v[14:15], v[44:45], s[18:19], v[8:9] op_sel_hi:[1,0,1]
	s_nop 0
	v_cvt_pk_bf16_f32 v8, v14, v15
	v_cvt_pk_bf16_f32 v9, v0, v1
	global_store_dwordx2 v[12:13], v[8:9], off
	s_nop 1
	v_mov_b32_e32 v8, v248
	v_mov_b32_e32 v9, v249
	v_mov_b32_e32 v10, v250
	v_mov_b32_e32 v11, v251
	v_mul_f32_e32 v0, v0, v0
	v_fmac_f32_e32 v0, v1, v1
	v_pk_fma_f32 v[16:17], v[42:43], s[18:19], v[10:11] op_sel_hi:[1,0,1]
	v_pk_fma_f32 v[18:19], v[40:41], s[18:19], v[8:9] op_sel_hi:[1,0,1]
	s_nop 0
	v_cvt_pk_bf16_f32 v8, v18, v19
	v_cvt_pk_bf16_f32 v9, v16, v17
	global_store_dwordx2 v[12:13], v[8:9], off offset:32
	s_nop 1
	v_mov_b32_e32 v8, v252
	v_mov_b32_e32 v9, v253
	v_mov_b32_e32 v10, v254
	v_mov_b32_e32 v11, v255
	v_mul_f32_e32 v1, v19, v19
	v_fmac_f32_e32 v1, v18, v18
	v_pk_fma_f32 v[20:21], v[38:39], s[18:19], v[10:11] op_sel_hi:[1,0,1]
	v_pk_fma_f32 v[22:23], v[36:37], s[18:19], v[8:9] op_sel_hi:[1,0,1]
	s_nop 0
	v_cvt_pk_bf16_f32 v8, v22, v23
	v_cvt_pk_bf16_f32 v9, v20, v21
	global_store_dwordx2 v[12:13], v[8:9], off offset:256
	s_nop 1
	v_mov_b32_e32 v8, v28
	v_mov_b32_e32 v9, v29
	v_mov_b32_e32 v10, v30
	v_mov_b32_e32 v11, v31
	v_mul_f32_e32 v4, v15, v15
	v_fmac_f32_e32 v4, v14, v14
	v_add_f32_e32 v0, v4, v0
	v_mul_f32_e32 v4, v16, v16
	v_fmac_f32_e32 v4, v17, v17
	v_add_f32_e32 v1, v1, v4
	v_add_f32_e32 v0, v0, v1
	v_mul_f32_e32 v1, v23, v23
	v_mul_f32_e32 v4, v20, v20
	v_fmac_f32_e32 v1, v22, v22
	v_fmac_f32_e32 v4, v21, v21
	v_add_f32_e32 v1, v1, v4
	v_add_f32_e32 v0, v0, v1
	v_pk_fma_f32 v[4:5], v[34:35], s[18:19], v[10:11] op_sel_hi:[1,0,1]
	v_pk_fma_f32 v[8:9], v[32:33], s[18:19], v[8:9] op_sel_hi:[1,0,1]
	v_mul_f32_e32 v10, v4, v4
	v_mul_f32_e32 v1, v9, v9
	v_fmac_f32_e32 v1, v8, v8
	v_fmac_f32_e32 v10, v5, v5
	v_add_f32_e32 v1, v1, v10
	v_add_f32_e32 v0, v0, v1
	ds_bpermute_b32 v1, v6, v0
	v_cvt_pk_bf16_f32 v6, v8, v9
	s_waitcnt lgkmcnt(0)
	v_add_f32_e32 v0, v0, v1
	ds_bpermute_b32 v1, v7, v0
	v_cvt_pk_bf16_f32 v7, v4, v5
	global_store_dwordx2 v[12:13], v[6:7], off offset:288
	s_and_saveexec_b64 s[28:29], s[0:1]
	s_cbranch_execz .LBB0_345
	v_lshl_add_u64 v[2:3], v[2:3], 2, s[12:13]
	s_waitcnt lgkmcnt(0)
	v_add_f32_e32 v0, v0, v1
	global_atomic_add_f32 v[2:3], v0, off

; __device__ __forceinline__ unsigned cvt_pk_bf16(float lo, float hi) { unsigned r; asm volatile("v_cvt_pk_bf16_f32 %0, %1, %2" : "=v"(r) : "v"(lo), "v"(hi)); return r; }
;     __device__ __forceinline__ void operator()(const f32x4 (&acc)[2][2][4][2], const Unit& u, int wr, int wc, int fr, int fq) const {
;     ...
;             for (int m = 0; m < 4; ++m) {
;                 const int row = row0 + ai * HALF + m * 16; const size_t off = (size_t)row * ldc + col0; float s = 0.f;
; #pragma unroll
;                 for (int bj = 0; bj < 2; ++bj)
; #pragma unroll
;                     for (int n = 0; n < 2; ++n) {
;                         f32x4 rsd;
;                         if (residb) { const u32x2v w = *(const u32x2v*)(residb + off + bj * HALF + n * 16); rsd = (f32x4){__builtin_bit_cast(float, w.x << 16), __builtin_bit_cast(float, w.x & 0xffff0000u), __builtin_bit_cast(float, w.y << 16), __builtin_bit_cast(float, w.y & 0xffff0000u)}; }
;                         else rsd = *(const f32x4*)(resid + off + bj * HALF + n * 16);
;                         const f32x4 v = rsd + acc[ai][bj][m][n] * asc;
;                         if (out) *(f32x4*)(out + off + bj * HALF + n * 16) = v;
;                         if (outb) { u32x2v w; w.x = cvt_pk_bf16(v[0], v[1]); w.y = cvt_pk_bf16(v[2], v[3]); *(u32x2v*)(outb + off + bj * HALF + n * 16) = w; }
;                         s += (v[0] * v[0] + v[1] * v[1]) + (v[2] * v[2] + v[3] * v[3]);
;                     }
;                 s += __shfl_xor(s, 16); s += __shfl_xor(s, 32);
;                 if (fq == 0) atomicAdd(ss + row, s);
;                 asm volatile("" ::: "memory");
.LBB0_647:
	v_lshl_add_u32 v142, s28, 8, v145
	v_lshl_or_b32 v140, s30, 8, v147
	v_ashrrev_i32_e32 v143, 31, v142
	v_ashrrev_i32_e32 v141, 31, v140
	v_lshlrev_b64 v[152:153], 12, v[142:143]
	v_lshl_add_u64 v[152:153], v[152:153], 0, v[140:141]
	v_lshlrev_b64 v[152:153], 1, v[152:153]
	v_lshl_add_u64 v[154:155], s[10:11], 0, v[152:153]
	global_load_dwordx2 v[164:165], v[154:155], off
	global_load_dwordx2 v[166:167], v[154:155], off offset:32
	global_load_dwordx2 v[168:169], v[154:155], off offset:256
	global_load_dwordx2 v[170:171], v[154:155], off offset:288
	v_add_co_u32_e32 v240, vcc, 0x20000, v154
	s_nop 1
	v_addc_co_u32_e32 v241, vcc, 0, v155, vcc
	global_load_dwordx2 v[172:173], v[240:241], off
	global_load_dwordx2 v[174:175], v[240:241], off offset:32
	global_load_dwordx2 v[176:177], v[240:241], off offset:256
	global_load_dwordx2 v[178:179], v[240:241], off offset:288
	v_add_co_u32_e32 v240, vcc, 0x40000, v154
	s_nop 1
	v_addc_co_u32_e32 v241, vcc, 0, v155, vcc
	global_load_dwordx2 v[180:181], v[240:241], off
	global_load_dwordx2 v[182:183], v[240:241], off offset:32
	global_load_dwordx2 v[184:185], v[240:241], off offset:256
	global_load_dwordx2 v[186:187], v[240:241], off offset:288
	v_add_co_u32_e32 v240, vcc, 0x60000, v154
	s_nop 1
	v_addc_co_u32_e32 v241, vcc, 0, v155, vcc
	global_load_dwordx2 v[188:189], v[240:241], off
	global_load_dwordx2 v[190:191], v[240:241], off offset:32
	global_load_dwordx2 v[192:193], v[240:241], off offset:256
	global_load_dwordx2 v[194:195], v[240:241], off offset:288
	v_add_co_u32_e32 v240, vcc, 0x100000, v154
	s_nop 1
	v_addc_co_u32_e32 v241, vcc, 0, v155, vcc
	global_load_dwordx2 v[196:197], v[240:241], off
	global_load_dwordx2 v[198:199], v[240:241], off offset:32
	global_load_dwordx2 v[200:201], v[240:241], off offset:256
	global_load_dwordx2 v[202:203], v[240:241], off offset:288
	v_add_co_u32_e32 v240, vcc, 0x120000, v154
	s_nop 1
	v_addc_co_u32_e32 v241, vcc, 0, v155, vcc
	global_load_dwordx2 v[204:205], v[240:241], off
	global_load_dwordx2 v[206:207], v[240:241], off offset:32
	global_load_dwordx2 v[208:209], v[240:241], off offset:256
	global_load_dwordx2 v[210:211], v[240:241], off offset:288
	v_add_co_u32_e32 v240, vcc, 0x140000, v154
	s_nop 1
	v_addc_co_u32_e32 v241, vcc, 0, v155, vcc
	global_load_dwordx2 v[212:213], v[240:241], off
	global_load_dwordx2 v[214:215], v[240:241], off offset:32
	global_load_dwordx2 v[224:225], v[240:241], off offset:256
	global_load_dwordx2 v[226:227], v[240:241], off offset:288
	v_add_co_u32_e32 v240, vcc, 0x160000, v154
	s_nop 1
	v_addc_co_u32_e32 v241, vcc, 0, v155, vcc
	global_load_dwordx2 v[228:229], v[240:241], off
	global_load_dwordx2 v[230:231], v[240:241], off offset:32
	global_load_dwordx2 v[232:233], v[240:241], off offset:256
	global_load_dwordx2 v[234:235], v[240:241], off offset:288
	s_waitcnt vmcnt(28)
	v_mov_b32_e32 v156, v164
	v_mov_b32_e32 v157, v165
	v_lshl_add_u64 v[152:153], s[12:13], 0, v[152:153]
	v_lshlrev_b32_e32 v158, 16, v156
	v_and_b32_e32 v159, 0xffff0000, v156
	v_lshlrev_b32_e32 v156, 16, v157
	v_and_b32_e32 v157, 0xffff0000, v157
	v_pk_add_f32 v[126:127], v[126:127], v[156:157]
	v_pk_add_f32 v[124:125], v[124:125], v[158:159]
	s_nop 0
	v_cvt_pk_bf16_f32 v156, v124, v125
	v_cvt_pk_bf16_f32 v157, v126, v127
	v_mov_b32_e32 v158, v166
	v_mov_b32_e32 v159, v167
	v_mul_f32_e32 v125, v125, v125
	global_store_dwordx2 v[152:153], v[156:157], off
	v_mul_f32_e32 v126, v126, v126
	v_fmac_f32_e32 v125, v124, v124
	v_fmac_f32_e32 v126, v127, v127
	v_add_f32_e32 v124, v125, v126
	v_lshlrev_b32_e32 v156, 16, v158
	v_and_b32_e32 v157, 0xffff0000, v158
	v_lshlrev_b32_e32 v158, 16, v159
	v_and_b32_e32 v159, 0xffff0000, v159
	v_pk_add_f32 v[122:123], v[122:123], v[158:159]
	v_pk_add_f32 v[120:121], v[120:121], v[156:157]
	s_nop 0
	v_cvt_pk_bf16_f32 v156, v120, v121
	v_cvt_pk_bf16_f32 v157, v122, v123
	v_mov_b32_e32 v158, v168
	v_mov_b32_e32 v159, v169
	v_mul_f32_e32 v121, v121, v121
	global_store_dwordx2 v[152:153], v[156:157], off offset:32
	v_mul_f32_e32 v122, v122, v122
	v_fmac_f32_e32 v121, v120, v120
	v_fmac_f32_e32 v122, v123, v123
	v_add_f32_e32 v120, v121, v122
	v_add_f32_e32 v120, v124, v120
	v_lshlrev_b32_e32 v156, 16, v158
	v_and_b32_e32 v157, 0xffff0000, v158
	v_lshlrev_b32_e32 v158, 16, v159
	v_and_b32_e32 v159, 0xffff0000, v159
	v_pk_add_f32 v[118:119], v[118:119], v[158:159]
	v_pk_add_f32 v[156:157], v[116:117], v[156:157]
	v_and_b32_e32 v117, 64, v151
	v_cvt_pk_bf16_f32 v158, v156, v157
	v_cvt_pk_bf16_f32 v159, v118, v119
	v_mov_b32_e32 v154, v170
	v_mov_b32_e32 v155, v171
	v_mul_f32_e32 v121, v157, v157
	v_mul_f32_e32 v118, v118, v118
	v_fmac_f32_e32 v121, v156, v156
	v_fmac_f32_e32 v118, v119, v119
	v_add_f32_e32 v118, v121, v118
	v_add_f32_e32 v122, v120, v118
	v_xor_b32_e32 v116, 16, v151
	v_add_u32_e32 v117, 64, v117
	v_cmp_lt_i32_e32 vcc, v116, v117
	global_store_dwordx2 v[152:153], v[158:159], off offset:256
	v_lshlrev_b32_e32 v118, 16, v154
	v_and_b32_e32 v119, 0xffff0000, v154
	v_lshlrev_b32_e32 v120, 16, v155
	v_and_b32_e32 v121, 0xffff0000, v155
	v_pk_add_f32 v[120:121], v[114:115], v[120:121]
	v_pk_add_f32 v[118:119], v[112:113], v[118:119]
	v_mul_f32_e32 v113, v120, v120
	v_mul_f32_e32 v112, v119, v119
	v_fmac_f32_e32 v112, v118, v118
	v_fmac_f32_e32 v113, v121, v121
	v_cndmask_b32_e32 v116, v151, v116, vcc
	v_add_f32_e32 v112, v112, v113
	v_lshlrev_b32_e32 v116, 2, v116
	v_add_f32_e32 v112, v122, v112
	ds_bpermute_b32 v113, v116, v112
	v_xor_b32_e32 v114, 32, v151
	v_cmp_lt_i32_e32 vcc, v114, v117
	v_cvt_pk_bf16_f32 v118, v118, v119
	v_cvt_pk_bf16_f32 v119, v120, v121
	s_waitcnt lgkmcnt(0)
	v_add_f32_e32 v112, v112, v113
	global_store_dwordx2 v[152:153], v[118:119], off offset:288
	v_cndmask_b32_e32 v114, v151, v114, vcc
	v_lshlrev_b32_e32 v114, 2, v114
	ds_bpermute_b32 v113, v114, v112
	s_and_saveexec_b64 s[28:29], s[0:1]
	s_cbranch_execz .LBB0_649
	v_lshl_add_u64 v[118:119], v[142:143], 2, s[14:15]
	s_waitcnt lgkmcnt(0)
	v_add_f32_e32 v112, v112, v113
	global_atomic_add_f32 v[118:119], v112, off
; __device__ __forceinline__ unsigned cvt_pk_bf16(float lo, float hi) { unsigned r; asm volatile("v_cvt_pk_bf16_f32 %0, %1, %2" : "=v"(r) : "v"(lo), "v"(hi)); return r; }
;     __device__ __forceinline__ void operator()(const f32x4 (&acc)[2][2][4][2], const Unit& u, int wr, int wc, int fr, int fq) const {
;     ...
;             for (int m = 0; m < 4; ++m) {
;                 const int row = row0 + ai * HALF + m * 16; const size_t off = (size_t)row * ldc + col0; float s = 0.f;
; #pragma unroll
;                 for (int bj = 0; bj < 2; ++bj)
; #pragma unroll
;                     for (int n = 0; n < 2; ++n) {
;                         f32x4 rsd;
;                         if (residb) { const u32x2v w = *(const u32x2v*)(residb + off + bj * HALF + n * 16); rsd = (f32x4){__builtin_bit_cast(float, w.x << 16), __builtin_bit_cast(float, w.x & 0xffff0000u), __builtin_bit_cast(float, w.y << 16), __builtin_bit_cast(float, w.y & 0xffff0000u)}; }
;                         else rsd = *(const f32x4*)(resid + off + bj * HALF + n * 16);
;                         const f32x4 v = rsd + acc[ai][bj][m][n] * asc;
;                         if (out) *(f32x4*)(out + off + bj * HALF + n * 16) = v;
;                         if (outb) { u32x2v w; w.x = cvt_pk_bf16(v[0], v[1]); w.y = cvt_pk_bf16(v[2], v[3]); *(u32x2v*)(outb + off + bj * HALF + n * 16) = w; }
;                         s += (v[0] * v[0] + v[1] * v[1]) + (v[2] * v[2] + v[3] * v[3]);
;                     }
;                 s += __shfl_xor(s, 16); s += __shfl_xor(s, 32);
;                 if (fq == 0) atomicAdd(ss + row, s);
;                 asm volatile("" ::: "memory");
.LBB0_649:
	s_or_b64 exec, exec, s[28:29]
	v_or_b32_e32 v112, 16, v142
	s_waitcnt lgkmcnt(0)
	v_ashrrev_i32_e32 v113, 31, v112
	v_lshlrev_b64 v[118:119], 12, v[112:113]
	v_lshl_add_u64 v[118:119], v[118:119], 0, v[140:141]
	v_lshlrev_b64 v[118:119], 1, v[118:119]
	v_lshl_add_u64 v[120:121], s[10:11], 0, v[118:119]
	s_waitcnt vmcnt(28)
	v_mov_b32_e32 v122, v172
	v_mov_b32_e32 v123, v173
	v_lshl_add_u64 v[118:119], s[12:13], 0, v[118:119]
	v_lshlrev_b32_e32 v124, 16, v122
	v_and_b32_e32 v125, 0xffff0000, v122
	v_lshlrev_b32_e32 v122, 16, v123
	v_and_b32_e32 v123, 0xffff0000, v123
	v_pk_add_f32 v[110:111], v[110:111], v[122:123]
	v_pk_add_f32 v[108:109], v[108:109], v[124:125]
	s_nop 0
	v_cvt_pk_bf16_f32 v122, v108, v109
	v_cvt_pk_bf16_f32 v123, v110, v111
	v_mov_b32_e32 v124, v174
	v_mov_b32_e32 v125, v175
	v_mul_f32_e32 v109, v109, v109
	global_store_dwordx2 v[118:119], v[122:123], off
	v_mul_f32_e32 v110, v110, v110
	v_fmac_f32_e32 v109, v108, v108
	v_fmac_f32_e32 v110, v111, v111
	v_add_f32_e32 v108, v109, v110
	v_lshlrev_b32_e32 v122, 16, v124
	v_and_b32_e32 v123, 0xffff0000, v124
	v_lshlrev_b32_e32 v124, 16, v125
	v_and_b32_e32 v125, 0xffff0000, v125
	v_pk_add_f32 v[106:107], v[106:107], v[124:125]
	v_pk_add_f32 v[104:105], v[104:105], v[122:123]
	s_nop 0
	v_cvt_pk_bf16_f32 v122, v104, v105
	v_cvt_pk_bf16_f32 v123, v106, v107
	v_mov_b32_e32 v124, v176
	v_mov_b32_e32 v125, v177
	v_mul_f32_e32 v105, v105, v105
	global_store_dwordx2 v[118:119], v[122:123], off offset:32
	v_mul_f32_e32 v106, v106, v106
	v_fmac_f32_e32 v105, v104, v104
	v_fmac_f32_e32 v106, v107, v107
	v_add_f32_e32 v104, v105, v106
	v_add_f32_e32 v104, v108, v104
	v_lshlrev_b32_e32 v122, 16, v124
	v_and_b32_e32 v123, 0xffff0000, v124
	v_lshlrev_b32_e32 v124, 16, v125
	v_and_b32_e32 v125, 0xffff0000, v125
	v_pk_add_f32 v[102:103], v[102:103], v[124:125]
	v_pk_add_f32 v[100:101], v[100:101], v[122:123]
	s_nop 0
	v_cvt_pk_bf16_f32 v122, v100, v101
	v_cvt_pk_bf16_f32 v123, v102, v103
	v_mov_b32_e32 v120, v178
	v_mov_b32_e32 v121, v179
	v_mul_f32_e32 v101, v101, v101
	v_mul_f32_e32 v102, v102, v102
	v_fmac_f32_e32 v101, v100, v100
	v_fmac_f32_e32 v102, v103, v103
	v_add_f32_e32 v100, v101, v102
	v_add_f32_e32 v104, v104, v100
	global_store_dwordx2 v[118:119], v[122:123], off offset:256
	v_lshlrev_b32_e32 v100, 16, v120
	v_and_b32_e32 v101, 0xffff0000, v120
	v_lshlrev_b32_e32 v102, 16, v121
	v_and_b32_e32 v103, 0xffff0000, v121
	v_pk_add_f32 v[98:99], v[98:99], v[102:103]
	v_pk_add_f32 v[100:101], v[96:97], v[100:101]
	v_mul_f32_e32 v97, v98, v98
	v_mul_f32_e32 v96, v101, v101
	v_fmac_f32_e32 v96, v100, v100
	v_fmac_f32_e32 v97, v99, v99
	v_add_f32_e32 v96, v96, v97
	v_add_f32_e32 v96, v104, v96
	ds_bpermute_b32 v97, v116, v96
	v_cvt_pk_bf16_f32 v100, v100, v101
	v_cvt_pk_bf16_f32 v101, v98, v99
	global_store_dwordx2 v[118:119], v[100:101], off offset:288
	s_waitcnt lgkmcnt(0)
	v_add_f32_e32 v96, v96, v97
	ds_bpermute_b32 v97, v114, v96
	s_and_saveexec_b64 s[28:29], s[0:1]
	s_cbranch_execz .LBB0_651
	v_lshl_add_u64 v[98:99], v[112:113], 2, s[14:15]
	s_waitcnt lgkmcnt(0)
	v_add_f32_e32 v96, v96, v97
	global_atomic_add_f32 v[98:99], v96, off
.LBB0_651:
	s_or_b64 exec, exec, s[28:29]
	v_or_b32_e32 v96, 32, v142
	s_waitcnt lgkmcnt(0)
	v_ashrrev_i32_e32 v97, 31, v96
	v_lshlrev_b64 v[98:99], 12, v[96:97]
	v_lshl_add_u64 v[98:99], v[98:99], 0, v[140:141]
	v_lshlrev_b64 v[98:99], 1, v[98:99]
	v_lshl_add_u64 v[100:101], s[10:11], 0, v[98:99]
	s_waitcnt vmcnt(28)
	v_mov_b32_e32 v102, v180
	v_mov_b32_e32 v103, v181
	v_lshl_add_u64 v[98:99], s[12:13], 0, v[98:99]
	v_lshlrev_b32_e32 v104, 16, v102
	v_and_b32_e32 v105, 0xffff0000, v102
	v_lshlrev_b32_e32 v102, 16, v103
	v_and_b32_e32 v103, 0xffff0000, v103
	v_pk_add_f32 v[94:95], v[94:95], v[102:103]
	v_pk_add_f32 v[92:93], v[92:93], v[104:105]
	s_nop 0
	v_cvt_pk_bf16_f32 v102, v92, v93
	v_cvt_pk_bf16_f32 v103, v94, v95
	v_mov_b32_e32 v104, v182
	v_mov_b32_e32 v105, v183
	v_mul_f32_e32 v93, v93, v93
	global_store_dwordx2 v[98:99], v[102:103], off
	v_mul_f32_e32 v94, v94, v94
	v_fmac_f32_e32 v93, v92, v92
	v_fmac_f32_e32 v94, v95, v95
	v_add_f32_e32 v92, v93, v94
	v_lshlrev_b32_e32 v102, 16, v104
	v_and_b32_e32 v103, 0xffff0000, v104
	v_lshlrev_b32_e32 v104, 16, v105
	v_and_b32_e32 v105, 0xffff0000, v105
	v_pk_add_f32 v[90:91], v[90:91], v[104:105]
	v_pk_add_f32 v[88:89], v[88:89], v[102:103]
	s_nop 0
	v_cvt_pk_bf16_f32 v102, v88, v89
	v_cvt_pk_bf16_f32 v103, v90, v91
	v_mov_b32_e32 v104, v184
	v_mov_b32_e32 v105, v185
	v_mul_f32_e32 v89, v89, v89
	global_store_dwordx2 v[98:99], v[102:103], off offset:32
	v_mul_f32_e32 v90, v90, v90
	v_fmac_f32_e32 v89, v88, v88
	v_fmac_f32_e32 v90, v91, v91
	v_add_f32_e32 v88, v89, v90
	v_add_f32_e32 v88, v92, v88
	v_lshlrev_b32_e32 v102, 16, v104
	v_and_b32_e32 v103, 0xffff0000, v104
	v_lshlrev_b32_e32 v104, 16, v105
	v_and_b32_e32 v105, 0xffff0000, v105
	v_pk_add_f32 v[86:87], v[86:87], v[104:105]
	v_pk_add_f32 v[84:85], v[84:85], v[102:103]
	s_nop 0
	v_cvt_pk_bf16_f32 v102, v84, v85
	v_cvt_pk_bf16_f32 v103, v86, v87
	v_mov_b32_e32 v100, v186
	v_mov_b32_e32 v101, v187
	v_mul_f32_e32 v85, v85, v85
	v_mul_f32_e32 v86, v86, v86
	v_fmac_f32_e32 v85, v84, v84
	v_fmac_f32_e32 v86, v87, v87
	v_add_f32_e32 v84, v85, v86
	v_add_f32_e32 v88, v88, v84
	global_store_dwordx2 v[98:99], v[102:103], off offset:256
	v_lshlrev_b32_e32 v84, 16, v100
	v_and_b32_e32 v85, 0xffff0000, v100
	v_lshlrev_b32_e32 v86, 16, v101
	v_and_b32_e32 v87, 0xffff0000, v101
	v_pk_add_f32 v[82:83], v[82:83], v[86:87]
	v_pk_add_f32 v[84:85], v[80:81], v[84:85]
	v_mul_f32_e32 v81, v82, v82
	v_mul_f32_e32 v80, v85, v85
	v_fmac_f32_e32 v80, v84, v84
	v_fmac_f32_e32 v81, v83, v83
	v_add_f32_e32 v80, v80, v81
	v_add_f32_e32 v80, v88, v80
	ds_bpermute_b32 v81, v116, v80
	v_cvt_pk_bf16_f32 v84, v84, v85
	v_cvt_pk_bf16_f32 v85, v82, v83
	global_store_dwordx2 v[98:99], v[84:85], off offset:288
	s_waitcnt lgkmcnt(0)
	v_add_f32_e32 v80, v80, v81
	ds_bpermute_b32 v81, v114, v80
	s_and_saveexec_b64 s[28:29], s[0:1]
	s_cbranch_execz .LBB0_653
	v_lshl_add_u64 v[82:83], v[96:97], 2, s[14:15]
	s_waitcnt lgkmcnt(0)
	v_add_f32_e32 v80, v80, v81
	global_atomic_add_f32 v[82:83], v80, off
; __device__ __forceinline__ unsigned cvt_pk_bf16(float lo, float hi) { unsigned r; asm volatile("v_cvt_pk_bf16_f32 %0, %1, %2" : "=v"(r) : "v"(lo), "v"(hi)); return r; }
;     __device__ __forceinline__ void operator()(const f32x4 (&acc)[2][2][4][2], const Unit& u, int wr, int wc, int fr, int fq) const {
;     ...
;             for (int m = 0; m < 4; ++m) {
;                 const int row = row0 + ai * HALF + m * 16; const size_t off = (size_t)row * ldc + col0; float s = 0.f;
; #pragma unroll
;                 for (int bj = 0; bj < 2; ++bj)
; #pragma unroll
;                     for (int n = 0; n < 2; ++n) {
;                         f32x4 rsd;
;                         if (residb) { const u32x2v w = *(const u32x2v*)(residb + off + bj * HALF + n * 16); rsd = (f32x4){__builtin_bit_cast(float, w.x << 16), __builtin_bit_cast(float, w.x & 0xffff0000u), __builtin_bit_cast(float, w.y << 16), __builtin_bit_cast(float, w.y & 0xffff0000u)}; }
;                         else rsd = *(const f32x4*)(resid + off + bj * HALF + n * 16);
;                         const f32x4 v = rsd + acc[ai][bj][m][n] * asc;
;                         if (out) *(f32x4*)(out + off + bj * HALF + n * 16) = v;
;                         if (outb) { u32x2v w; w.x = cvt_pk_bf16(v[0], v[1]); w.y = cvt_pk_bf16(v[2], v[3]); *(u32x2v*)(outb + off + bj * HALF + n * 16) = w; }
;                         s += (v[0] * v[0] + v[1] * v[1]) + (v[2] * v[2] + v[3] * v[3]);
;                     }
;                 s += __shfl_xor(s, 16); s += __shfl_xor(s, 32);
;                 if (fq == 0) atomicAdd(ss + row, s);
;                 asm volatile("" ::: "memory");
.LBB0_653:
	s_or_b64 exec, exec, s[28:29]
	v_or_b32_e32 v80, 48, v142
	s_waitcnt lgkmcnt(0)
	v_ashrrev_i32_e32 v81, 31, v80
	v_lshlrev_b64 v[82:83], 12, v[80:81]
	v_lshl_add_u64 v[82:83], v[82:83], 0, v[140:141]
	v_lshlrev_b64 v[82:83], 1, v[82:83]
	v_lshl_add_u64 v[84:85], s[10:11], 0, v[82:83]
	s_waitcnt vmcnt(28)
	v_mov_b32_e32 v86, v188
	v_mov_b32_e32 v87, v189
	v_lshl_add_u64 v[82:83], s[12:13], 0, v[82:83]
	v_lshlrev_b32_e32 v88, 16, v86
	v_and_b32_e32 v89, 0xffff0000, v86
	v_lshlrev_b32_e32 v86, 16, v87
	v_and_b32_e32 v87, 0xffff0000, v87
	v_pk_add_f32 v[78:79], v[78:79], v[86:87]
	v_pk_add_f32 v[76:77], v[76:77], v[88:89]
	s_nop 0
	v_cvt_pk_bf16_f32 v86, v76, v77
	v_cvt_pk_bf16_f32 v87, v78, v79
	v_mov_b32_e32 v88, v190
	v_mov_b32_e32 v89, v191
	v_mul_f32_e32 v77, v77, v77
	global_store_dwordx2 v[82:83], v[86:87], off
	v_mul_f32_e32 v78, v78, v78
	v_fmac_f32_e32 v77, v76, v76
	v_fmac_f32_e32 v78, v79, v79
	v_add_f32_e32 v76, v77, v78
	v_lshlrev_b32_e32 v86, 16, v88
	v_and_b32_e32 v87, 0xffff0000, v88
	v_lshlrev_b32_e32 v88, 16, v89
	v_and_b32_e32 v89, 0xffff0000, v89
	v_pk_add_f32 v[74:75], v[74:75], v[88:89]
	v_pk_add_f32 v[72:73], v[72:73], v[86:87]
	s_nop 0
	v_cvt_pk_bf16_f32 v86, v72, v73
	v_cvt_pk_bf16_f32 v87, v74, v75
	v_mov_b32_e32 v88, v192
	v_mov_b32_e32 v89, v193
	v_mul_f32_e32 v73, v73, v73
	global_store_dwordx2 v[82:83], v[86:87], off offset:32
	v_mul_f32_e32 v74, v74, v74
	v_fmac_f32_e32 v73, v72, v72
	v_fmac_f32_e32 v74, v75, v75
	v_add_f32_e32 v72, v73, v74
	v_add_f32_e32 v72, v76, v72
	v_lshlrev_b32_e32 v86, 16, v88
	v_and_b32_e32 v87, 0xffff0000, v88
	v_lshlrev_b32_e32 v88, 16, v89
	v_and_b32_e32 v89, 0xffff0000, v89
	v_pk_add_f32 v[70:71], v[70:71], v[88:89]
	v_pk_add_f32 v[68:69], v[68:69], v[86:87]
	s_nop 0
	v_cvt_pk_bf16_f32 v86, v68, v69
	v_cvt_pk_bf16_f32 v87, v70, v71
	v_mov_b32_e32 v84, v194
	v_mov_b32_e32 v85, v195
	v_mul_f32_e32 v69, v69, v69
	v_mul_f32_e32 v70, v70, v70
	v_fmac_f32_e32 v69, v68, v68
	v_fmac_f32_e32 v70, v71, v71
	v_add_f32_e32 v68, v69, v70
	v_add_f32_e32 v72, v72, v68
	global_store_dwordx2 v[82:83], v[86:87], off offset:256
	v_lshlrev_b32_e32 v68, 16, v84
	v_and_b32_e32 v69, 0xffff0000, v84
	v_lshlrev_b32_e32 v70, 16, v85
	v_and_b32_e32 v71, 0xffff0000, v85
	v_pk_add_f32 v[66:67], v[66:67], v[70:71]
	v_pk_add_f32 v[68:69], v[64:65], v[68:69]
	v_mul_f32_e32 v65, v66, v66
	v_mul_f32_e32 v64, v69, v69
	v_fmac_f32_e32 v64, v68, v68
	v_fmac_f32_e32 v65, v67, v67
	v_add_f32_e32 v64, v64, v65
	v_add_f32_e32 v64, v72, v64
	ds_bpermute_b32 v65, v116, v64
	v_cvt_pk_bf16_f32 v68, v68, v69
	v_cvt_pk_bf16_f32 v69, v66, v67
	global_store_dwordx2 v[82:83], v[68:69], off offset:288
	s_waitcnt lgkmcnt(0)
	v_add_f32_e32 v64, v64, v65
	ds_bpermute_b32 v65, v114, v64
	s_and_saveexec_b64 s[28:29], s[0:1]
	s_cbranch_execz .LBB0_655
	v_lshl_add_u64 v[66:67], v[80:81], 2, s[14:15]
	s_waitcnt lgkmcnt(0)
	v_add_f32_e32 v64, v64, v65
	global_atomic_add_f32 v[66:67], v64, off
.LBB0_655:
	s_or_b64 exec, exec, s[28:29]
	v_add_u32_e32 v64, 0x80, v142
	s_waitcnt lgkmcnt(0)
	v_ashrrev_i32_e32 v65, 31, v64
	v_lshlrev_b64 v[66:67], 12, v[64:65]
	v_lshl_add_u64 v[66:67], v[66:67], 0, v[140:141]
	v_lshlrev_b64 v[66:67], 1, v[66:67]
	v_lshl_add_u64 v[68:69], s[10:11], 0, v[66:67]
	s_waitcnt vmcnt(28)
	v_mov_b32_e32 v70, v196
	v_mov_b32_e32 v71, v197
	v_lshl_add_u64 v[66:67], s[12:13], 0, v[66:67]
	v_lshlrev_b32_e32 v72, 16, v70
	v_and_b32_e32 v73, 0xffff0000, v70
	v_lshlrev_b32_e32 v70, 16, v71
	v_and_b32_e32 v71, 0xffff0000, v71
	v_pk_add_f32 v[62:63], v[62:63], v[70:71]
	v_pk_add_f32 v[60:61], v[60:61], v[72:73]
	s_nop 0
	v_cvt_pk_bf16_f32 v70, v60, v61
	v_cvt_pk_bf16_f32 v71, v62, v63
	v_mov_b32_e32 v72, v198
	v_mov_b32_e32 v73, v199
	v_mul_f32_e32 v61, v61, v61
	global_store_dwordx2 v[66:67], v[70:71], off
	v_mul_f32_e32 v62, v62, v62
	v_fmac_f32_e32 v61, v60, v60
	v_fmac_f32_e32 v62, v63, v63
	v_add_f32_e32 v60, v61, v62
	v_lshlrev_b32_e32 v70, 16, v72
	v_and_b32_e32 v71, 0xffff0000, v72
	v_lshlrev_b32_e32 v72, 16, v73
	v_and_b32_e32 v73, 0xffff0000, v73
	v_pk_add_f32 v[58:59], v[58:59], v[72:73]
	v_pk_add_f32 v[56:57], v[56:57], v[70:71]
	s_nop 0
	v_cvt_pk_bf16_f32 v70, v56, v57
	v_cvt_pk_bf16_f32 v71, v58, v59
	v_mov_b32_e32 v72, v200
	v_mov_b32_e32 v73, v201
	v_mul_f32_e32 v57, v57, v57
	global_store_dwordx2 v[66:67], v[70:71], off offset:32
	v_mul_f32_e32 v58, v58, v58
	v_fmac_f32_e32 v57, v56, v56
	v_fmac_f32_e32 v58, v59, v59
	v_add_f32_e32 v56, v57, v58
	v_add_f32_e32 v56, v60, v56
	v_lshlrev_b32_e32 v70, 16, v72
	v_and_b32_e32 v71, 0xffff0000, v72
	v_lshlrev_b32_e32 v72, 16, v73
	v_and_b32_e32 v73, 0xffff0000, v73
	v_pk_add_f32 v[54:55], v[54:55], v[72:73]
	v_pk_add_f32 v[52:53], v[52:53], v[70:71]
	s_nop 0
	v_cvt_pk_bf16_f32 v70, v52, v53
	v_cvt_pk_bf16_f32 v71, v54, v55
	v_mov_b32_e32 v68, v202
	v_mov_b32_e32 v69, v203
	v_mul_f32_e32 v53, v53, v53
	v_mul_f32_e32 v54, v54, v54
	v_fmac_f32_e32 v53, v52, v52
	v_fmac_f32_e32 v54, v55, v55
	v_add_f32_e32 v52, v53, v54
	v_add_f32_e32 v56, v56, v52
	global_store_dwordx2 v[66:67], v[70:71], off offset:256
	v_lshlrev_b32_e32 v52, 16, v68
	v_and_b32_e32 v53, 0xffff0000, v68
	v_lshlrev_b32_e32 v54, 16, v69
	v_and_b32_e32 v55, 0xffff0000, v69
	v_pk_add_f32 v[50:51], v[50:51], v[54:55]
	v_pk_add_f32 v[52:53], v[48:49], v[52:53]
	v_mul_f32_e32 v49, v50, v50
	v_mul_f32_e32 v48, v53, v53
	v_fmac_f32_e32 v48, v52, v52
	v_fmac_f32_e32 v49, v51, v51
	v_add_f32_e32 v48, v48, v49
	v_add_f32_e32 v48, v56, v48
	ds_bpermute_b32 v49, v116, v48
	v_cvt_pk_bf16_f32 v52, v52, v53
	v_cvt_pk_bf16_f32 v53, v50, v51
	global_store_dwordx2 v[66:67], v[52:53], off offset:288
	s_waitcnt lgkmcnt(0)
	v_add_f32_e32 v48, v48, v49
	ds_bpermute_b32 v49, v114, v48
	s_and_saveexec_b64 s[28:29], s[0:1]
	s_cbranch_execz .LBB0_657
	v_lshl_add_u64 v[50:51], v[64:65], 2, s[14:15]
	s_waitcnt lgkmcnt(0)
	v_add_f32_e32 v48, v48, v49
	global_atomic_add_f32 v[50:51], v48, off
; __device__ __forceinline__ unsigned cvt_pk_bf16(float lo, float hi) { unsigned r; asm volatile("v_cvt_pk_bf16_f32 %0, %1, %2" : "=v"(r) : "v"(lo), "v"(hi)); return r; }
;     __device__ __forceinline__ void operator()(const f32x4 (&acc)[2][2][4][2], const Unit& u, int wr, int wc, int fr, int fq) const {
;     ...
;             for (int m = 0; m < 4; ++m) {
;                 const int row = row0 + ai * HALF + m * 16; const size_t off = (size_t)row * ldc + col0; float s = 0.f;
; #pragma unroll
;                 for (int bj = 0; bj < 2; ++bj)
; #pragma unroll
;                     for (int n = 0; n < 2; ++n) {
;                         f32x4 rsd;
;                         if (residb) { const u32x2v w = *(const u32x2v*)(residb + off + bj * HALF + n * 16); rsd = (f32x4){__builtin_bit_cast(float, w.x << 16), __builtin_bit_cast(float, w.x & 0xffff0000u), __builtin_bit_cast(float, w.y << 16), __builtin_bit_cast(float, w.y & 0xffff0000u)}; }
;                         else rsd = *(const f32x4*)(resid + off + bj * HALF + n * 16);
;                         const f32x4 v = rsd + acc[ai][bj][m][n] * asc;
;                         if (out) *(f32x4*)(out + off + bj * HALF + n * 16) = v;
;                         if (outb) { u32x2v w; w.x = cvt_pk_bf16(v[0], v[1]); w.y = cvt_pk_bf16(v[2], v[3]); *(u32x2v*)(outb + off + bj * HALF + n * 16) = w; }
;                         s += (v[0] * v[0] + v[1] * v[1]) + (v[2] * v[2] + v[3] * v[3]);
;                     }
;                 s += __shfl_xor(s, 16); s += __shfl_xor(s, 32);
;                 if (fq == 0) atomicAdd(ss + row, s);
;                 asm volatile("" ::: "memory");
.LBB0_657:
	s_or_b64 exec, exec, s[28:29]
	v_add_u32_e32 v48, 0x90, v142
	s_waitcnt lgkmcnt(0)
	v_ashrrev_i32_e32 v49, 31, v48
	v_lshlrev_b64 v[50:51], 12, v[48:49]
	v_lshl_add_u64 v[50:51], v[50:51], 0, v[140:141]
	v_lshlrev_b64 v[50:51], 1, v[50:51]
	v_lshl_add_u64 v[52:53], s[10:11], 0, v[50:51]
	s_waitcnt vmcnt(28)
	v_mov_b32_e32 v54, v204
	v_mov_b32_e32 v55, v205
	v_lshl_add_u64 v[50:51], s[12:13], 0, v[50:51]
	v_lshlrev_b32_e32 v56, 16, v54
	v_and_b32_e32 v57, 0xffff0000, v54
	v_lshlrev_b32_e32 v54, 16, v55
	v_and_b32_e32 v55, 0xffff0000, v55
	v_pk_add_f32 v[46:47], v[46:47], v[54:55]
	v_pk_add_f32 v[44:45], v[44:45], v[56:57]
	s_nop 0
	v_cvt_pk_bf16_f32 v54, v44, v45
	v_cvt_pk_bf16_f32 v55, v46, v47
	v_mov_b32_e32 v56, v206
	v_mov_b32_e32 v57, v207
	v_mul_f32_e32 v45, v45, v45
	global_store_dwordx2 v[50:51], v[54:55], off
	v_mul_f32_e32 v46, v46, v46
	v_fmac_f32_e32 v45, v44, v44
	v_fmac_f32_e32 v46, v47, v47
	v_add_f32_e32 v44, v45, v46
	v_lshlrev_b32_e32 v54, 16, v56
	v_and_b32_e32 v55, 0xffff0000, v56
	v_lshlrev_b32_e32 v56, 16, v57
	v_and_b32_e32 v57, 0xffff0000, v57
	v_pk_add_f32 v[42:43], v[42:43], v[56:57]
	v_pk_add_f32 v[40:41], v[40:41], v[54:55]
	s_nop 0
	v_cvt_pk_bf16_f32 v54, v40, v41
	v_cvt_pk_bf16_f32 v55, v42, v43
	v_mov_b32_e32 v56, v208
	v_mov_b32_e32 v57, v209
	v_mul_f32_e32 v41, v41, v41
	global_store_dwordx2 v[50:51], v[54:55], off offset:32
	v_mul_f32_e32 v42, v42, v42
	v_fmac_f32_e32 v41, v40, v40
	v_fmac_f32_e32 v42, v43, v43
	v_add_f32_e32 v40, v41, v42
	v_add_f32_e32 v40, v44, v40
	v_lshlrev_b32_e32 v54, 16, v56
	v_and_b32_e32 v55, 0xffff0000, v56
	v_lshlrev_b32_e32 v56, 16, v57
	v_and_b32_e32 v57, 0xffff0000, v57
	v_pk_add_f32 v[38:39], v[38:39], v[56:57]
	v_pk_add_f32 v[36:37], v[36:37], v[54:55]
	s_nop 0
	v_cvt_pk_bf16_f32 v54, v36, v37
	v_cvt_pk_bf16_f32 v55, v38, v39
	v_mov_b32_e32 v52, v210
	v_mov_b32_e32 v53, v211
	v_mul_f32_e32 v37, v37, v37
	v_mul_f32_e32 v38, v38, v38
	v_fmac_f32_e32 v37, v36, v36
	v_fmac_f32_e32 v38, v39, v39
	v_add_f32_e32 v36, v37, v38
	v_add_f32_e32 v40, v40, v36
	global_store_dwordx2 v[50:51], v[54:55], off offset:256
	v_lshlrev_b32_e32 v36, 16, v52
	v_and_b32_e32 v37, 0xffff0000, v52
	v_lshlrev_b32_e32 v38, 16, v53
	v_and_b32_e32 v39, 0xffff0000, v53
	v_pk_add_f32 v[34:35], v[34:35], v[38:39]
	v_pk_add_f32 v[36:37], v[32:33], v[36:37]
	v_mul_f32_e32 v33, v34, v34
	v_mul_f32_e32 v32, v37, v37
	v_fmac_f32_e32 v32, v36, v36
	v_fmac_f32_e32 v33, v35, v35
	v_add_f32_e32 v32, v32, v33
	v_add_f32_e32 v32, v40, v32
	ds_bpermute_b32 v33, v116, v32
	v_cvt_pk_bf16_f32 v36, v36, v37
	v_cvt_pk_bf16_f32 v37, v34, v35
	global_store_dwordx2 v[50:51], v[36:37], off offset:288
	s_waitcnt lgkmcnt(0)
	v_add_f32_e32 v32, v32, v33
	ds_bpermute_b32 v33, v114, v32
	s_and_saveexec_b64 s[28:29], s[0:1]
	s_cbranch_execz .LBB0_659
	v_lshl_add_u64 v[34:35], v[48:49], 2, s[14:15]
	s_waitcnt lgkmcnt(0)
	v_add_f32_e32 v32, v32, v33
	global_atomic_add_f32 v[34:35], v32, off
; __device__ __forceinline__ unsigned cvt_pk_bf16(float lo, float hi) { unsigned r; asm volatile("v_cvt_pk_bf16_f32 %0, %1, %2" : "=v"(r) : "v"(lo), "v"(hi)); return r; }
;     __device__ __forceinline__ void operator()(const f32x4 (&acc)[2][2][4][2], const Unit& u, int wr, int wc, int fr, int fq) const {
;     ...
;                 const int row = row0 + ai * HALF + m * 16; const size_t off = (size_t)row * ldc + col0; float s = 0.f;
; #pragma unroll
;                 for (int bj = 0; bj < 2; ++bj)
; #pragma unroll
;                     for (int n = 0; n < 2; ++n) {
;                         f32x4 rsd;
;                         if (residb) { const u32x2v w = *(const u32x2v*)(residb + off + bj * HALF + n * 16); rsd = (f32x4){__builtin_bit_cast(float, w.x << 16), __builtin_bit_cast(float, w.x & 0xffff0000u), __builtin_bit_cast(float, w.y << 16), __builtin_bit_cast(float, w.y & 0xffff0000u)}; }
;                         else rsd = *(const f32x4*)(resid + off + bj * HALF + n * 16);
;                         const f32x4 v = rsd + acc[ai][bj][m][n] * asc;
;                         if (out) *(f32x4*)(out + off + bj * HALF + n * 16) = v;
;                         if (outb) { u32x2v w; w.x = cvt_pk_bf16(v[0], v[1]); w.y = cvt_pk_bf16(v[2], v[3]); *(u32x2v*)(outb + off + bj * HALF + n * 16) = w; }
;                         s += (v[0] * v[0] + v[1] * v[1]) + (v[2] * v[2] + v[3] * v[3]);
;                     }
;                 s += __shfl_xor(s, 16); s += __shfl_xor(s, 32);
;                 if (fq == 0) atomicAdd(ss + row, s);
.LBB0_659:
	s_or_b64 exec, exec, s[28:29]
	v_add_u32_e32 v32, 0xa0, v142
	s_waitcnt lgkmcnt(0)
	v_ashrrev_i32_e32 v33, 31, v32
	v_lshlrev_b64 v[34:35], 12, v[32:33]
	v_lshl_add_u64 v[34:35], v[34:35], 0, v[140:141]
	v_lshlrev_b64 v[34:35], 1, v[34:35]
	v_lshl_add_u64 v[36:37], s[10:11], 0, v[34:35]
	s_waitcnt vmcnt(28)
	v_mov_b32_e32 v38, v212
	v_mov_b32_e32 v39, v213
	v_lshl_add_u64 v[34:35], s[12:13], 0, v[34:35]
	v_lshlrev_b32_e32 v40, 16, v38
	v_and_b32_e32 v41, 0xffff0000, v38
	v_lshlrev_b32_e32 v38, 16, v39
	v_and_b32_e32 v39, 0xffff0000, v39
	v_pk_add_f32 v[30:31], v[30:31], v[38:39]
	v_pk_add_f32 v[28:29], v[28:29], v[40:41]
	s_nop 0
	v_cvt_pk_bf16_f32 v38, v28, v29
	v_cvt_pk_bf16_f32 v39, v30, v31
	v_mov_b32_e32 v40, v214
	v_mov_b32_e32 v41, v215
	v_mul_f32_e32 v29, v29, v29
	global_store_dwordx2 v[34:35], v[38:39], off
	v_mul_f32_e32 v30, v30, v30
	v_fmac_f32_e32 v29, v28, v28
	v_fmac_f32_e32 v30, v31, v31
	v_add_f32_e32 v28, v29, v30
	v_lshlrev_b32_e32 v38, 16, v40
	v_and_b32_e32 v39, 0xffff0000, v40
	v_lshlrev_b32_e32 v40, 16, v41
	v_and_b32_e32 v41, 0xffff0000, v41
	v_pk_add_f32 v[26:27], v[26:27], v[40:41]
	v_pk_add_f32 v[24:25], v[24:25], v[38:39]
	s_nop 0
	v_cvt_pk_bf16_f32 v38, v24, v25
	v_cvt_pk_bf16_f32 v39, v26, v27
	v_mov_b32_e32 v40, v224
	v_mov_b32_e32 v41, v225
	v_mul_f32_e32 v25, v25, v25
	global_store_dwordx2 v[34:35], v[38:39], off offset:32
	v_mul_f32_e32 v26, v26, v26
	v_fmac_f32_e32 v25, v24, v24
	v_fmac_f32_e32 v26, v27, v27
	v_add_f32_e32 v24, v25, v26
	v_add_f32_e32 v24, v28, v24
	v_lshlrev_b32_e32 v38, 16, v40
	v_and_b32_e32 v39, 0xffff0000, v40
	v_lshlrev_b32_e32 v40, 16, v41
	v_and_b32_e32 v41, 0xffff0000, v41
	v_pk_add_f32 v[22:23], v[22:23], v[40:41]
	v_pk_add_f32 v[20:21], v[20:21], v[38:39]
	s_nop 0
	v_cvt_pk_bf16_f32 v38, v20, v21
	v_cvt_pk_bf16_f32 v39, v22, v23
	v_mov_b32_e32 v36, v226
	v_mov_b32_e32 v37, v227
	v_mul_f32_e32 v21, v21, v21
	v_mul_f32_e32 v22, v22, v22
	v_fmac_f32_e32 v21, v20, v20
	v_fmac_f32_e32 v22, v23, v23
	v_add_f32_e32 v20, v21, v22
	v_add_f32_e32 v24, v24, v20
	global_store_dwordx2 v[34:35], v[38:39], off offset:256
	v_lshlrev_b32_e32 v20, 16, v36
	v_and_b32_e32 v21, 0xffff0000, v36
	v_lshlrev_b32_e32 v22, 16, v37
	v_and_b32_e32 v23, 0xffff0000, v37
	v_pk_add_f32 v[18:19], v[18:19], v[22:23]
	v_pk_add_f32 v[20:21], v[16:17], v[20:21]
	v_mul_f32_e32 v17, v18, v18
	v_mul_f32_e32 v16, v21, v21
	v_fmac_f32_e32 v16, v20, v20
	v_fmac_f32_e32 v17, v19, v19
	v_add_f32_e32 v16, v16, v17
	v_add_f32_e32 v16, v24, v16
	ds_bpermute_b32 v17, v116, v16
	v_cvt_pk_bf16_f32 v20, v20, v21
	v_cvt_pk_bf16_f32 v21, v18, v19
	global_store_dwordx2 v[34:35], v[20:21], off offset:288
	s_waitcnt lgkmcnt(0)
	v_add_f32_e32 v16, v16, v17
	ds_bpermute_b32 v17, v114, v16
	s_and_saveexec_b64 s[28:29], s[0:1]
	s_cbranch_execz .LBB0_661
	v_lshl_add_u64 v[18:19], v[32:33], 2, s[14:15]
	s_waitcnt lgkmcnt(0)
	v_add_f32_e32 v16, v16, v17
	global_atomic_add_f32 v[18:19], v16, off
.LBB0_661:
	s_or_b64 exec, exec, s[28:29]
	v_add_u32_e32 v16, 0xb0, v142
	s_waitcnt lgkmcnt(0)
	v_ashrrev_i32_e32 v17, 31, v16
	v_lshlrev_b64 v[18:19], 12, v[16:17]
	v_lshl_add_u64 v[18:19], v[18:19], 0, v[140:141]
	v_lshlrev_b64 v[18:19], 1, v[18:19]
	v_lshl_add_u64 v[20:21], s[10:11], 0, v[18:19]
	s_waitcnt vmcnt(28)
	v_mov_b32_e32 v22, v228
	v_mov_b32_e32 v23, v229
	v_lshl_add_u64 v[18:19], s[12:13], 0, v[18:19]
	v_lshlrev_b32_e32 v24, 16, v22
	v_and_b32_e32 v25, 0xffff0000, v22
	v_lshlrev_b32_e32 v22, 16, v23
	v_and_b32_e32 v23, 0xffff0000, v23
	v_pk_add_f32 v[14:15], v[14:15], v[22:23]
	v_pk_add_f32 v[12:13], v[12:13], v[24:25]
	s_nop 0
	v_cvt_pk_bf16_f32 v22, v12, v13
	v_cvt_pk_bf16_f32 v23, v14, v15
	v_mov_b32_e32 v24, v230
	v_mov_b32_e32 v25, v231
	v_mul_f32_e32 v13, v13, v13
	global_store_dwordx2 v[18:19], v[22:23], off
	v_mul_f32_e32 v14, v14, v14
	v_fmac_f32_e32 v13, v12, v12
	v_fmac_f32_e32 v14, v15, v15
	v_add_f32_e32 v12, v13, v14
	v_lshlrev_b32_e32 v22, 16, v24
	v_and_b32_e32 v23, 0xffff0000, v24
	v_lshlrev_b32_e32 v24, 16, v25
	v_and_b32_e32 v25, 0xffff0000, v25
	v_pk_add_f32 v[10:11], v[10:11], v[24:25]
	v_pk_add_f32 v[8:9], v[8:9], v[22:23]
	s_nop 0
	v_cvt_pk_bf16_f32 v22, v8, v9
	v_cvt_pk_bf16_f32 v23, v10, v11
	v_mov_b32_e32 v24, v232
	v_mov_b32_e32 v25, v233
	v_mul_f32_e32 v9, v9, v9
	global_store_dwordx2 v[18:19], v[22:23], off offset:32
	v_mul_f32_e32 v10, v10, v10
	v_fmac_f32_e32 v9, v8, v8
	v_fmac_f32_e32 v10, v11, v11
	v_add_f32_e32 v8, v9, v10
	v_add_f32_e32 v8, v12, v8
	v_lshlrev_b32_e32 v22, 16, v24
	v_and_b32_e32 v23, 0xffff0000, v24
	v_lshlrev_b32_e32 v24, 16, v25
	v_and_b32_e32 v25, 0xffff0000, v25
	v_pk_add_f32 v[6:7], v[6:7], v[24:25]
	v_pk_add_f32 v[4:5], v[4:5], v[22:23]
	s_nop 0
	v_cvt_pk_bf16_f32 v22, v4, v5
	v_cvt_pk_bf16_f32 v23, v6, v7
	v_mov_b32_e32 v20, v234
	v_mov_b32_e32 v21, v235
	v_mul_f32_e32 v5, v5, v5
	v_mul_f32_e32 v6, v6, v6
	v_fmac_f32_e32 v5, v4, v4
	v_fmac_f32_e32 v6, v7, v7
	v_add_f32_e32 v4, v5, v6
	v_add_f32_e32 v8, v8, v4
	global_store_dwordx2 v[18:19], v[22:23], off offset:256
	v_lshlrev_b32_e32 v4, 16, v20
	v_and_b32_e32 v5, 0xffff0000, v20
	v_lshlrev_b32_e32 v6, 16, v21
	v_and_b32_e32 v7, 0xffff0000, v21
	v_pk_add_f32 v[2:3], v[2:3], v[6:7]
	v_pk_add_f32 v[4:5], v[0:1], v[4:5]
	v_mul_f32_e32 v1, v2, v2
	v_mul_f32_e32 v0, v5, v5
	v_fmac_f32_e32 v0, v4, v4
	v_fmac_f32_e32 v1, v3, v3
	v_add_f32_e32 v0, v0, v1
	v_add_f32_e32 v0, v8, v0
	ds_bpermute_b32 v1, v116, v0
	v_cvt_pk_bf16_f32 v4, v4, v5
	v_cvt_pk_bf16_f32 v5, v2, v3
	global_store_dwordx2 v[18:19], v[4:5], off offset:288
	s_waitcnt lgkmcnt(0)
	v_add_f32_e32 v0, v0, v1
	ds_bpermute_b32 v1, v114, v0
	s_and_saveexec_b64 s[28:29], s[0:1]
	s_cbranch_execz .LBB0_663
	v_lshl_add_u64 v[2:3], v[16:17], 2, s[14:15]
	s_waitcnt lgkmcnt(0)
	v_add_f32_e32 v0, v0, v1
	global_atomic_add_f32 v[2:3], v0, off
